# double-buffered A fragments also in phases 1,5,8 GEMM loops
# speedup vs baseline: 1.0758x; 1.0053x over previous
.LBB0_131:
	s_andn2_b64 vcc, exec, s[0:1]
	s_mov_b64 s[0:1], -1
	s_cbranch_vccnz .LBB0_127
	s_mul_hi_i32 s0, s11, 0x66666667
	s_lshr_b32 s1, s0, 31
	s_ashr_i32 s0, s0, 9
	s_add_i32 s0, s0, s1
	s_mul_i32 s1, s0, 0x500
	s_sub_i32 s1, s11, s1
	s_mul_i32 s4, s1, 0x6667
	s_lshr_b32 s5, s4, 31
	s_ashr_i32 s4, s4, 18
	s_add_i32 s4, s4, s5
	s_mul_i32 s5, s4, 10
	s_sub_i32 s1, s1, s5
	s_lshl_b32 s4, s4, 7
	s_mul_i32 s0, s0, 10
	s_sext_i32_i16 s1, s1
	v_or_b32_e32 v0, s4, v112
	s_add_i32 s0, s0, s1
	v_ashrrev_i32_e32 v1, 31, v0
	s_lshl_b32 s5, s0, 7
	v_lshlrev_b64 v[0:1], 11, v[0:1]
	v_lshl_add_u64 v[108:109], v[104:105], 0, v[0:1]
	v_or_b32_e32 v0, s5, v112
	v_ashrrev_i32_e32 v1, 31, v0
	v_lshlrev_b64 v[0:1], 11, v[0:1]
	v_lshl_add_u64 v[110:111], v[106:107], 0, v[0:1]
	v_readfirstlane_b32 s100, v108
	v_readfirstlane_b32 s101, v109
	v_readfirstlane_b32 s98, v110
	v_readfirstlane_b32 s99, v111
	s_nop 1
	v_subrev_u32_e32 v108, s100, v108
	v_subrev_u32_e32 v110, s98, v110
	v_add_u32_e32 v109, 0x10000, v108
	v_add_u32_e32 v111, 0x10000, v110
	v_add_u32_e32 v163, 0x20000, v108
	v_add_u32_e32 v214, 0x20000, v110
	v_add_u32_e32 v165, 0x30000, v108
	v_add_u32_e32 v215, 0x30000, v110
	global_load_dwordx4 v[36:39], v108, s[100:101] offset:0
	global_load_dwordx4 v[60:63], v110, s[98:99] offset:0
	global_load_dwordx4 v[40:43], v109, s[100:101] offset:0
	global_load_dwordx4 v[64:67], v111, s[98:99] offset:0
	global_load_dwordx4 v[44:47], v163, s[100:101] offset:0
	global_load_dwordx4 v[76:79], v214, s[98:99] offset:0
	global_load_dwordx4 v[48:51], v165, s[100:101] offset:0
	global_load_dwordx4 v[80:83], v215, s[98:99] offset:0
	global_load_dwordx4 v[118:121], v108, s[100:101] offset:128
	global_load_dwordx4 v[140:143], v110, s[98:99] offset:128
	global_load_dwordx4 v[122:125], v109, s[100:101] offset:128
	global_load_dwordx4 v[144:147], v111, s[98:99] offset:128
	global_load_dwordx4 v[126:129], v163, s[100:101] offset:128
	global_load_dwordx4 v[148:151], v214, s[98:99] offset:128
	global_load_dwordx4 v[130:133], v165, s[100:101] offset:128
	global_load_dwordx4 v[152:155], v215, s[98:99] offset:128
	v_mov_b32_e32 v92, 0
	v_mov_b32_e32 v93, 0
	v_mov_b32_e32 v94, 0
	v_mov_b32_e32 v95, 0
	v_mov_b32_e32 v88, 0
	v_mov_b32_e32 v89, 0
	v_mov_b32_e32 v90, 0
	v_mov_b32_e32 v91, 0
	v_mov_b32_e32 v84, 0
	v_mov_b32_e32 v85, 0
	v_mov_b32_e32 v86, 0
	v_mov_b32_e32 v87, 0
	v_mov_b32_e32 v0, 0
	v_mov_b32_e32 v1, 0
	v_mov_b32_e32 v2, 0
	v_mov_b32_e32 v3, 0
	v_mov_b32_e32 v28, 0
	v_mov_b32_e32 v29, 0
	v_mov_b32_e32 v30, 0
	v_mov_b32_e32 v31, 0
	v_mov_b32_e32 v72, 0
	v_mov_b32_e32 v73, 0
	v_mov_b32_e32 v74, 0
	v_mov_b32_e32 v75, 0
	v_mov_b32_e32 v68, 0
	v_mov_b32_e32 v69, 0
	v_mov_b32_e32 v70, 0
	v_mov_b32_e32 v71, 0
	v_mov_b32_e32 v4, 0
	v_mov_b32_e32 v5, 0
	v_mov_b32_e32 v6, 0
	v_mov_b32_e32 v7, 0
	v_mov_b32_e32 v32, 0
	v_mov_b32_e32 v33, 0
	v_mov_b32_e32 v34, 0
	v_mov_b32_e32 v35, 0
	v_mov_b32_e32 v56, 0
	v_mov_b32_e32 v57, 0
	v_mov_b32_e32 v58, 0
	v_mov_b32_e32 v59, 0
	v_mov_b32_e32 v52, 0
	v_mov_b32_e32 v53, 0
	v_mov_b32_e32 v54, 0
	v_mov_b32_e32 v55, 0
	v_mov_b32_e32 v8, 0
	v_mov_b32_e32 v9, 0
	v_mov_b32_e32 v10, 0
	v_mov_b32_e32 v11, 0
	v_mov_b32_e32 v16, 0
	v_mov_b32_e32 v17, 0
	v_mov_b32_e32 v18, 0
	v_mov_b32_e32 v19, 0
	v_mov_b32_e32 v20, 0
	v_mov_b32_e32 v21, 0
	v_mov_b32_e32 v22, 0
	v_mov_b32_e32 v23, 0
	v_mov_b32_e32 v24, 0
	v_mov_b32_e32 v25, 0
	v_mov_b32_e32 v26, 0
	v_mov_b32_e32 v27, 0
	v_mov_b32_e32 v12, 0
	v_mov_b32_e32 v13, 0
	v_mov_b32_e32 v14, 0
	v_mov_b32_e32 v15, 0
	s_barrier
	s_waitcnt vmcnt(8)
	ds_write_b128 v103, v[36:39]
	ds_write_b128 v103, v[60:63] offset:16384
	ds_write_b128 v103, v[40:43] offset:4096
	ds_write_b128 v103, v[64:67] offset:20480
	ds_write_b128 v103, v[44:47] offset:8192
	ds_write_b128 v103, v[76:79] offset:24576
	ds_write_b128 v103, v[48:51] offset:12288
	ds_write_b128 v103, v[80:83] offset:28672
	s_waitcnt lgkmcnt(0)
	global_load_dwordx4 v[36:39], v108, s[100:101] offset:256
	global_load_dwordx4 v[60:63], v110, s[98:99] offset:256
	global_load_dwordx4 v[40:43], v109, s[100:101] offset:256
	global_load_dwordx4 v[64:67], v111, s[98:99] offset:256
	global_load_dwordx4 v[44:47], v163, s[100:101] offset:256
	global_load_dwordx4 v[76:79], v214, s[98:99] offset:256
	global_load_dwordx4 v[48:51], v165, s[100:101] offset:256
	global_load_dwordx4 v[80:83], v215, s[98:99] offset:256
	s_barrier
	s_mov_b32 s94, 6
.Lgm_p1_loop:
	ds_read_b128 v[194:197], v115 offset:16384
	ds_read_b128 v[156:159], v114
	ds_read_b128 v[198:201], v115 offset:18432
	ds_read_b128 v[202:205], v115 offset:20480
	ds_read_b128 v[206:209], v115 offset:22528
	ds_read_b128 v[166:169], v114 offset:2048
	ds_read_b128 v[170:173], v114 offset:4096
	ds_read_b128 v[174:177], v114 offset:6144
	s_setprio 1
	s_waitcnt lgkmcnt(3)
	v_mfma_f32_16x16x32_bf16 v[92:95], v[194:197], v[156:159], v[92:95]
	ds_read_b128 v[210:213], v117 offset:16384
	v_mfma_f32_16x16x32_bf16 v[88:91], v[198:201], v[156:159], v[88:91]
	ds_read_b128 v[178:181], v116
	v_mfma_f32_16x16x32_bf16 v[84:87], v[202:205], v[156:159], v[84:87]
	ds_read_b128 v[232:235], v117 offset:18432
	v_mfma_f32_16x16x32_bf16 v[0:3], v[206:209], v[156:159], v[0:3]
	ds_read_b128 v[236:239], v117 offset:20480
	s_waitcnt lgkmcnt(4)
	v_mfma_f32_16x16x32_bf16 v[28:31], v[194:197], v[166:169], v[28:31]
	ds_read_b128 v[240:243], v117 offset:22528
	v_mfma_f32_16x16x32_bf16 v[72:75], v[198:201], v[166:169], v[72:75]
	ds_read_b128 v[182:185], v116 offset:2048
	v_mfma_f32_16x16x32_bf16 v[68:71], v[202:205], v[166:169], v[68:71]
	ds_read_b128 v[186:189], v116 offset:4096
	v_mfma_f32_16x16x32_bf16 v[4:7], v[206:209], v[166:169], v[4:7]
	ds_read_b128 v[190:193], v116 offset:6144
	v_mfma_f32_16x16x32_bf16 v[32:35], v[194:197], v[170:173], v[32:35]
	s_waitcnt vmcnt(8)
	ds_write_b128 v103, v[118:121] offset:32768
	v_mfma_f32_16x16x32_bf16 v[56:59], v[198:201], v[170:173], v[56:59]
	ds_write_b128 v103, v[140:143] offset:49152
	v_mfma_f32_16x16x32_bf16 v[52:55], v[202:205], v[170:173], v[52:55]
	ds_write_b128 v103, v[122:125] offset:36864
	v_mfma_f32_16x16x32_bf16 v[8:11], v[206:209], v[170:173], v[8:11]
	ds_write_b128 v103, v[144:147] offset:53248
	v_mfma_f32_16x16x32_bf16 v[16:19], v[194:197], v[174:177], v[16:19]
	ds_write_b128 v103, v[126:129] offset:40960
	v_mfma_f32_16x16x32_bf16 v[20:23], v[198:201], v[174:177], v[20:23]
	ds_write_b128 v103, v[148:151] offset:57344
	v_mfma_f32_16x16x32_bf16 v[24:27], v[202:205], v[174:177], v[24:27]
	ds_write_b128 v103, v[130:133] offset:45056
	v_mfma_f32_16x16x32_bf16 v[12:15], v[206:209], v[174:177], v[12:15]
	s_waitcnt lgkmcnt(8)
	ds_write_b128 v103, v[152:155] offset:61440
	v_mfma_f32_16x16x32_bf16 v[92:95], v[210:213], v[178:181], v[92:95]
	v_mfma_f32_16x16x32_bf16 v[88:91], v[232:235], v[178:181], v[88:91]
	v_mfma_f32_16x16x32_bf16 v[84:87], v[236:239], v[178:181], v[84:87]
	v_mfma_f32_16x16x32_bf16 v[0:3], v[240:243], v[178:181], v[0:3]
	s_waitcnt lgkmcnt(8)
	v_mfma_f32_16x16x32_bf16 v[28:31], v[210:213], v[182:185], v[28:31]
	s_waitcnt lgkmcnt(0)
	global_load_dwordx4 v[118:121], v108, s[100:101] offset:384
	v_mfma_f32_16x16x32_bf16 v[72:75], v[232:235], v[182:185], v[72:75]
	global_load_dwordx4 v[140:143], v110, s[98:99] offset:384
	v_mfma_f32_16x16x32_bf16 v[68:71], v[236:239], v[182:185], v[68:71]
	global_load_dwordx4 v[122:125], v109, s[100:101] offset:384
	v_mfma_f32_16x16x32_bf16 v[4:7], v[240:243], v[182:185], v[4:7]
	global_load_dwordx4 v[144:147], v111, s[98:99] offset:384
	v_mfma_f32_16x16x32_bf16 v[32:35], v[210:213], v[186:189], v[32:35]
	global_load_dwordx4 v[126:129], v163, s[100:101] offset:384
	v_mfma_f32_16x16x32_bf16 v[56:59], v[232:235], v[186:189], v[56:59]
	global_load_dwordx4 v[148:151], v214, s[98:99] offset:384
	v_mfma_f32_16x16x32_bf16 v[52:55], v[236:239], v[186:189], v[52:55]
	global_load_dwordx4 v[130:133], v165, s[100:101] offset:384
	v_mfma_f32_16x16x32_bf16 v[8:11], v[240:243], v[186:189], v[8:11]
	global_load_dwordx4 v[152:155], v215, s[98:99] offset:384
	v_mfma_f32_16x16x32_bf16 v[16:19], v[210:213], v[190:193], v[16:19]
	v_mfma_f32_16x16x32_bf16 v[20:23], v[232:235], v[190:193], v[20:23]
	v_mfma_f32_16x16x32_bf16 v[24:27], v[236:239], v[190:193], v[24:27]
	v_mfma_f32_16x16x32_bf16 v[12:15], v[240:243], v[190:193], v[12:15]
	s_setprio 0
	s_barrier
	ds_read_b128 v[194:197], v115 offset:49152
	ds_read_b128 v[156:159], v114 offset:32768
	ds_read_b128 v[198:201], v115 offset:51200
	ds_read_b128 v[202:205], v115 offset:53248
	ds_read_b128 v[206:209], v115 offset:55296
	ds_read_b128 v[166:169], v114 offset:34816
	ds_read_b128 v[170:173], v114 offset:36864
	ds_read_b128 v[174:177], v114 offset:38912
	s_setprio 1
	s_waitcnt lgkmcnt(3)
	v_mfma_f32_16x16x32_bf16 v[92:95], v[194:197], v[156:159], v[92:95]
	ds_read_b128 v[210:213], v117 offset:49152
	v_mfma_f32_16x16x32_bf16 v[88:91], v[198:201], v[156:159], v[88:91]
	ds_read_b128 v[178:181], v116 offset:32768
	v_mfma_f32_16x16x32_bf16 v[84:87], v[202:205], v[156:159], v[84:87]
	ds_read_b128 v[232:235], v117 offset:51200
	v_mfma_f32_16x16x32_bf16 v[0:3], v[206:209], v[156:159], v[0:3]
	ds_read_b128 v[236:239], v117 offset:53248
	s_waitcnt lgkmcnt(4)
	v_mfma_f32_16x16x32_bf16 v[28:31], v[194:197], v[166:169], v[28:31]
	ds_read_b128 v[240:243], v117 offset:55296
	v_mfma_f32_16x16x32_bf16 v[72:75], v[198:201], v[166:169], v[72:75]
	ds_read_b128 v[182:185], v116 offset:34816
	v_mfma_f32_16x16x32_bf16 v[68:71], v[202:205], v[166:169], v[68:71]
	ds_read_b128 v[186:189], v116 offset:36864
	v_mfma_f32_16x16x32_bf16 v[4:7], v[206:209], v[166:169], v[4:7]
	ds_read_b128 v[190:193], v116 offset:38912
	v_mfma_f32_16x16x32_bf16 v[32:35], v[194:197], v[170:173], v[32:35]
	s_waitcnt vmcnt(8)
	ds_write_b128 v103, v[36:39]
	v_mfma_f32_16x16x32_bf16 v[56:59], v[198:201], v[170:173], v[56:59]
	ds_write_b128 v103, v[60:63] offset:16384
	v_mfma_f32_16x16x32_bf16 v[52:55], v[202:205], v[170:173], v[52:55]
	ds_write_b128 v103, v[40:43] offset:4096
	v_mfma_f32_16x16x32_bf16 v[8:11], v[206:209], v[170:173], v[8:11]
	ds_write_b128 v103, v[64:67] offset:20480
	v_mfma_f32_16x16x32_bf16 v[16:19], v[194:197], v[174:177], v[16:19]
	ds_write_b128 v103, v[44:47] offset:8192
	v_mfma_f32_16x16x32_bf16 v[20:23], v[198:201], v[174:177], v[20:23]
	ds_write_b128 v103, v[76:79] offset:24576
	v_mfma_f32_16x16x32_bf16 v[24:27], v[202:205], v[174:177], v[24:27]
	ds_write_b128 v103, v[48:51] offset:12288
	v_mfma_f32_16x16x32_bf16 v[12:15], v[206:209], v[174:177], v[12:15]
	s_waitcnt lgkmcnt(8)
	ds_write_b128 v103, v[80:83] offset:28672
	v_mfma_f32_16x16x32_bf16 v[92:95], v[210:213], v[178:181], v[92:95]
	v_mfma_f32_16x16x32_bf16 v[88:91], v[232:235], v[178:181], v[88:91]
	v_mfma_f32_16x16x32_bf16 v[84:87], v[236:239], v[178:181], v[84:87]
	v_mfma_f32_16x16x32_bf16 v[0:3], v[240:243], v[178:181], v[0:3]
	s_waitcnt lgkmcnt(8)
	v_mfma_f32_16x16x32_bf16 v[28:31], v[210:213], v[182:185], v[28:31]
	s_waitcnt lgkmcnt(0)
	global_load_dwordx4 v[36:39], v108, s[100:101] offset:512
	v_mfma_f32_16x16x32_bf16 v[72:75], v[232:235], v[182:185], v[72:75]
	global_load_dwordx4 v[60:63], v110, s[98:99] offset:512
	v_mfma_f32_16x16x32_bf16 v[68:71], v[236:239], v[182:185], v[68:71]
	global_load_dwordx4 v[40:43], v109, s[100:101] offset:512
	v_mfma_f32_16x16x32_bf16 v[4:7], v[240:243], v[182:185], v[4:7]
	global_load_dwordx4 v[64:67], v111, s[98:99] offset:512
	v_mfma_f32_16x16x32_bf16 v[32:35], v[210:213], v[186:189], v[32:35]
	global_load_dwordx4 v[44:47], v163, s[100:101] offset:512
	v_mfma_f32_16x16x32_bf16 v[56:59], v[232:235], v[186:189], v[56:59]
	global_load_dwordx4 v[76:79], v214, s[98:99] offset:512
	v_mfma_f32_16x16x32_bf16 v[52:55], v[236:239], v[186:189], v[52:55]
	global_load_dwordx4 v[48:51], v165, s[100:101] offset:512
	v_mfma_f32_16x16x32_bf16 v[8:11], v[240:243], v[186:189], v[8:11]
	global_load_dwordx4 v[80:83], v215, s[98:99] offset:512
	v_mfma_f32_16x16x32_bf16 v[16:19], v[210:213], v[190:193], v[16:19]
	v_mfma_f32_16x16x32_bf16 v[20:23], v[232:235], v[190:193], v[20:23]
	v_mfma_f32_16x16x32_bf16 v[24:27], v[236:239], v[190:193], v[24:27]
	v_mfma_f32_16x16x32_bf16 v[12:15], v[240:243], v[190:193], v[12:15]
	s_setprio 0
	s_barrier
	s_add_u32 s100, s100, 0x100
	s_addc_u32 s101, s101, 0
	s_add_u32 s98, s98, 0x100
	s_addc_u32 s99, s99, 0
	s_sub_u32 s94, s94, 1
	s_cmp_lg_u32 s94, 0
	s_cbranch_scc1 .Lgm_p1_loop
	ds_read_b128 v[194:197], v115 offset:16384
	ds_read_b128 v[156:159], v114
	ds_read_b128 v[198:201], v115 offset:18432
	ds_read_b128 v[202:205], v115 offset:20480
	ds_read_b128 v[206:209], v115 offset:22528
	ds_read_b128 v[166:169], v114 offset:2048
	ds_read_b128 v[170:173], v114 offset:4096
	ds_read_b128 v[174:177], v114 offset:6144
	s_setprio 1
	s_waitcnt lgkmcnt(3)
	v_mfma_f32_16x16x32_bf16 v[92:95], v[194:197], v[156:159], v[92:95]
	ds_read_b128 v[210:213], v117 offset:16384
	v_mfma_f32_16x16x32_bf16 v[88:91], v[198:201], v[156:159], v[88:91]
	ds_read_b128 v[178:181], v116
	v_mfma_f32_16x16x32_bf16 v[84:87], v[202:205], v[156:159], v[84:87]
	ds_read_b128 v[232:235], v117 offset:18432
	v_mfma_f32_16x16x32_bf16 v[0:3], v[206:209], v[156:159], v[0:3]
	ds_read_b128 v[236:239], v117 offset:20480
	s_waitcnt lgkmcnt(4)
	v_mfma_f32_16x16x32_bf16 v[28:31], v[194:197], v[166:169], v[28:31]
	ds_read_b128 v[240:243], v117 offset:22528
	v_mfma_f32_16x16x32_bf16 v[72:75], v[198:201], v[166:169], v[72:75]
	ds_read_b128 v[182:185], v116 offset:2048
	v_mfma_f32_16x16x32_bf16 v[68:71], v[202:205], v[166:169], v[68:71]
	ds_read_b128 v[186:189], v116 offset:4096
	v_mfma_f32_16x16x32_bf16 v[4:7], v[206:209], v[166:169], v[4:7]
	ds_read_b128 v[190:193], v116 offset:6144
	v_mfma_f32_16x16x32_bf16 v[32:35], v[194:197], v[170:173], v[32:35]
	s_waitcnt vmcnt(8)
	ds_write_b128 v103, v[118:121] offset:32768
	v_mfma_f32_16x16x32_bf16 v[56:59], v[198:201], v[170:173], v[56:59]
	ds_write_b128 v103, v[140:143] offset:49152
	v_mfma_f32_16x16x32_bf16 v[52:55], v[202:205], v[170:173], v[52:55]
	ds_write_b128 v103, v[122:125] offset:36864
	v_mfma_f32_16x16x32_bf16 v[8:11], v[206:209], v[170:173], v[8:11]
	ds_write_b128 v103, v[144:147] offset:53248
	v_mfma_f32_16x16x32_bf16 v[16:19], v[194:197], v[174:177], v[16:19]
	ds_write_b128 v103, v[126:129] offset:40960
	v_mfma_f32_16x16x32_bf16 v[20:23], v[198:201], v[174:177], v[20:23]
	ds_write_b128 v103, v[148:151] offset:57344
	v_mfma_f32_16x16x32_bf16 v[24:27], v[202:205], v[174:177], v[24:27]
	ds_write_b128 v103, v[130:133] offset:45056
	v_mfma_f32_16x16x32_bf16 v[12:15], v[206:209], v[174:177], v[12:15]
	s_waitcnt lgkmcnt(8)
	ds_write_b128 v103, v[152:155] offset:61440
	v_mfma_f32_16x16x32_bf16 v[92:95], v[210:213], v[178:181], v[92:95]
	v_mfma_f32_16x16x32_bf16 v[88:91], v[232:235], v[178:181], v[88:91]
	v_mfma_f32_16x16x32_bf16 v[84:87], v[236:239], v[178:181], v[84:87]
	v_mfma_f32_16x16x32_bf16 v[0:3], v[240:243], v[178:181], v[0:3]
	s_waitcnt lgkmcnt(8)
	v_mfma_f32_16x16x32_bf16 v[28:31], v[210:213], v[182:185], v[28:31]
	s_waitcnt lgkmcnt(0)
	global_load_dwordx4 v[118:121], v108, s[100:101] offset:384
	v_mfma_f32_16x16x32_bf16 v[72:75], v[232:235], v[182:185], v[72:75]
	global_load_dwordx4 v[140:143], v110, s[98:99] offset:384
	v_mfma_f32_16x16x32_bf16 v[68:71], v[236:239], v[182:185], v[68:71]
	global_load_dwordx4 v[122:125], v109, s[100:101] offset:384
	v_mfma_f32_16x16x32_bf16 v[4:7], v[240:243], v[182:185], v[4:7]
	global_load_dwordx4 v[144:147], v111, s[98:99] offset:384
	v_mfma_f32_16x16x32_bf16 v[32:35], v[210:213], v[186:189], v[32:35]
	global_load_dwordx4 v[126:129], v163, s[100:101] offset:384
	v_mfma_f32_16x16x32_bf16 v[56:59], v[232:235], v[186:189], v[56:59]
	global_load_dwordx4 v[148:151], v214, s[98:99] offset:384
	v_mfma_f32_16x16x32_bf16 v[52:55], v[236:239], v[186:189], v[52:55]
	global_load_dwordx4 v[130:133], v165, s[100:101] offset:384
	v_mfma_f32_16x16x32_bf16 v[8:11], v[240:243], v[186:189], v[8:11]
	global_load_dwordx4 v[152:155], v215, s[98:99] offset:384
	v_mfma_f32_16x16x32_bf16 v[16:19], v[210:213], v[190:193], v[16:19]
	v_mfma_f32_16x16x32_bf16 v[20:23], v[232:235], v[190:193], v[20:23]
	v_mfma_f32_16x16x32_bf16 v[24:27], v[236:239], v[190:193], v[24:27]
	v_mfma_f32_16x16x32_bf16 v[12:15], v[240:243], v[190:193], v[12:15]
	s_setprio 0
	s_barrier
	ds_read_b128 v[194:197], v115 offset:49152
	ds_read_b128 v[156:159], v114 offset:32768
	ds_read_b128 v[198:201], v115 offset:51200
	ds_read_b128 v[202:205], v115 offset:53248
	ds_read_b128 v[206:209], v115 offset:55296
	ds_read_b128 v[166:169], v114 offset:34816
	ds_read_b128 v[170:173], v114 offset:36864
	ds_read_b128 v[174:177], v114 offset:38912
	s_setprio 1
	s_waitcnt lgkmcnt(3)
	v_mfma_f32_16x16x32_bf16 v[92:95], v[194:197], v[156:159], v[92:95]
	ds_read_b128 v[210:213], v117 offset:49152
	v_mfma_f32_16x16x32_bf16 v[88:91], v[198:201], v[156:159], v[88:91]
	ds_read_b128 v[178:181], v116 offset:32768
	v_mfma_f32_16x16x32_bf16 v[84:87], v[202:205], v[156:159], v[84:87]
	ds_read_b128 v[232:235], v117 offset:51200
	v_mfma_f32_16x16x32_bf16 v[0:3], v[206:209], v[156:159], v[0:3]
	ds_read_b128 v[236:239], v117 offset:53248
	s_waitcnt lgkmcnt(4)
	v_mfma_f32_16x16x32_bf16 v[28:31], v[194:197], v[166:169], v[28:31]
	ds_read_b128 v[240:243], v117 offset:55296
	v_mfma_f32_16x16x32_bf16 v[72:75], v[198:201], v[166:169], v[72:75]
	ds_read_b128 v[182:185], v116 offset:34816
	v_mfma_f32_16x16x32_bf16 v[68:71], v[202:205], v[166:169], v[68:71]
	ds_read_b128 v[186:189], v116 offset:36864
	v_mfma_f32_16x16x32_bf16 v[4:7], v[206:209], v[166:169], v[4:7]
	ds_read_b128 v[190:193], v116 offset:38912
	v_mfma_f32_16x16x32_bf16 v[32:35], v[194:197], v[170:173], v[32:35]
	s_waitcnt vmcnt(8)
	ds_write_b128 v103, v[36:39]
	v_mfma_f32_16x16x32_bf16 v[56:59], v[198:201], v[170:173], v[56:59]
	ds_write_b128 v103, v[60:63] offset:16384
	v_mfma_f32_16x16x32_bf16 v[52:55], v[202:205], v[170:173], v[52:55]
	ds_write_b128 v103, v[40:43] offset:4096
	v_mfma_f32_16x16x32_bf16 v[8:11], v[206:209], v[170:173], v[8:11]
	ds_write_b128 v103, v[64:67] offset:20480
	v_mfma_f32_16x16x32_bf16 v[16:19], v[194:197], v[174:177], v[16:19]
	ds_write_b128 v103, v[44:47] offset:8192
	v_mfma_f32_16x16x32_bf16 v[20:23], v[198:201], v[174:177], v[20:23]
	ds_write_b128 v103, v[76:79] offset:24576
	v_mfma_f32_16x16x32_bf16 v[24:27], v[202:205], v[174:177], v[24:27]
	ds_write_b128 v103, v[48:51] offset:12288
	v_mfma_f32_16x16x32_bf16 v[12:15], v[206:209], v[174:177], v[12:15]
	s_waitcnt lgkmcnt(8)
	ds_write_b128 v103, v[80:83] offset:28672
	v_mfma_f32_16x16x32_bf16 v[92:95], v[210:213], v[178:181], v[92:95]
	v_mfma_f32_16x16x32_bf16 v[88:91], v[232:235], v[178:181], v[88:91]
	v_mfma_f32_16x16x32_bf16 v[84:87], v[236:239], v[178:181], v[84:87]
	v_mfma_f32_16x16x32_bf16 v[0:3], v[240:243], v[178:181], v[0:3]
	s_waitcnt lgkmcnt(8)
	v_mfma_f32_16x16x32_bf16 v[28:31], v[210:213], v[182:185], v[28:31]
	v_mfma_f32_16x16x32_bf16 v[72:75], v[232:235], v[182:185], v[72:75]
	v_mfma_f32_16x16x32_bf16 v[68:71], v[236:239], v[182:185], v[68:71]
	v_mfma_f32_16x16x32_bf16 v[4:7], v[240:243], v[182:185], v[4:7]
	v_mfma_f32_16x16x32_bf16 v[32:35], v[210:213], v[186:189], v[32:35]
	v_mfma_f32_16x16x32_bf16 v[56:59], v[232:235], v[186:189], v[56:59]
	v_mfma_f32_16x16x32_bf16 v[52:55], v[236:239], v[186:189], v[52:55]
	v_mfma_f32_16x16x32_bf16 v[8:11], v[240:243], v[186:189], v[8:11]
	v_mfma_f32_16x16x32_bf16 v[16:19], v[210:213], v[190:193], v[16:19]
	v_mfma_f32_16x16x32_bf16 v[20:23], v[232:235], v[190:193], v[20:23]
	v_mfma_f32_16x16x32_bf16 v[24:27], v[236:239], v[190:193], v[24:27]
	v_mfma_f32_16x16x32_bf16 v[12:15], v[240:243], v[190:193], v[12:15]
	s_setprio 0
	s_waitcnt lgkmcnt(0)
	s_barrier
	ds_read_b128 v[194:197], v115 offset:16384
	ds_read_b128 v[156:159], v114
	ds_read_b128 v[198:201], v115 offset:18432
	ds_read_b128 v[202:205], v115 offset:20480
	ds_read_b128 v[206:209], v115 offset:22528
	ds_read_b128 v[166:169], v114 offset:2048
	ds_read_b128 v[170:173], v114 offset:4096
	ds_read_b128 v[174:177], v114 offset:6144
	s_setprio 1
	s_waitcnt lgkmcnt(3)
	v_mfma_f32_16x16x32_bf16 v[92:95], v[194:197], v[156:159], v[92:95]
	ds_read_b128 v[210:213], v117 offset:16384
	v_mfma_f32_16x16x32_bf16 v[88:91], v[198:201], v[156:159], v[88:91]
	ds_read_b128 v[178:181], v116
	v_mfma_f32_16x16x32_bf16 v[84:87], v[202:205], v[156:159], v[84:87]
	ds_read_b128 v[232:235], v117 offset:18432
	v_mfma_f32_16x16x32_bf16 v[0:3], v[206:209], v[156:159], v[0:3]
	ds_read_b128 v[236:239], v117 offset:20480
	s_waitcnt lgkmcnt(4)
	v_mfma_f32_16x16x32_bf16 v[28:31], v[194:197], v[166:169], v[28:31]
	ds_read_b128 v[240:243], v117 offset:22528
	v_mfma_f32_16x16x32_bf16 v[72:75], v[198:201], v[166:169], v[72:75]
	ds_read_b128 v[182:185], v116 offset:2048
	v_mfma_f32_16x16x32_bf16 v[68:71], v[202:205], v[166:169], v[68:71]
	ds_read_b128 v[186:189], v116 offset:4096
	v_mfma_f32_16x16x32_bf16 v[4:7], v[206:209], v[166:169], v[4:7]
	ds_read_b128 v[190:193], v116 offset:6144
	v_mfma_f32_16x16x32_bf16 v[32:35], v[194:197], v[170:173], v[32:35]
	s_waitcnt vmcnt(0)
	ds_write_b128 v103, v[118:121] offset:32768
	v_mfma_f32_16x16x32_bf16 v[56:59], v[198:201], v[170:173], v[56:59]
	ds_write_b128 v103, v[140:143] offset:49152
	v_mfma_f32_16x16x32_bf16 v[52:55], v[202:205], v[170:173], v[52:55]
	ds_write_b128 v103, v[122:125] offset:36864
	v_mfma_f32_16x16x32_bf16 v[8:11], v[206:209], v[170:173], v[8:11]
	ds_write_b128 v103, v[144:147] offset:53248
	v_mfma_f32_16x16x32_bf16 v[16:19], v[194:197], v[174:177], v[16:19]
	ds_write_b128 v103, v[126:129] offset:40960
	v_mfma_f32_16x16x32_bf16 v[20:23], v[198:201], v[174:177], v[20:23]
	ds_write_b128 v103, v[148:151] offset:57344
	v_mfma_f32_16x16x32_bf16 v[24:27], v[202:205], v[174:177], v[24:27]
	ds_write_b128 v103, v[130:133] offset:45056
	v_mfma_f32_16x16x32_bf16 v[12:15], v[206:209], v[174:177], v[12:15]
	s_waitcnt lgkmcnt(8)
	ds_write_b128 v103, v[152:155] offset:61440
	v_mfma_f32_16x16x32_bf16 v[92:95], v[210:213], v[178:181], v[92:95]
	v_mfma_f32_16x16x32_bf16 v[88:91], v[232:235], v[178:181], v[88:91]
	v_mfma_f32_16x16x32_bf16 v[84:87], v[236:239], v[178:181], v[84:87]
	v_mfma_f32_16x16x32_bf16 v[0:3], v[240:243], v[178:181], v[0:3]
	s_waitcnt lgkmcnt(8)
	v_mfma_f32_16x16x32_bf16 v[28:31], v[210:213], v[182:185], v[28:31]
	v_mfma_f32_16x16x32_bf16 v[72:75], v[232:235], v[182:185], v[72:75]
	v_mfma_f32_16x16x32_bf16 v[68:71], v[236:239], v[182:185], v[68:71]
	v_mfma_f32_16x16x32_bf16 v[4:7], v[240:243], v[182:185], v[4:7]
	v_mfma_f32_16x16x32_bf16 v[32:35], v[210:213], v[186:189], v[32:35]
	v_mfma_f32_16x16x32_bf16 v[56:59], v[232:235], v[186:189], v[56:59]
	v_mfma_f32_16x16x32_bf16 v[52:55], v[236:239], v[186:189], v[52:55]
	v_mfma_f32_16x16x32_bf16 v[8:11], v[240:243], v[186:189], v[8:11]
	v_mfma_f32_16x16x32_bf16 v[16:19], v[210:213], v[190:193], v[16:19]
	v_mfma_f32_16x16x32_bf16 v[20:23], v[232:235], v[190:193], v[20:23]
	v_mfma_f32_16x16x32_bf16 v[24:27], v[236:239], v[190:193], v[24:27]
	v_mfma_f32_16x16x32_bf16 v[12:15], v[240:243], v[190:193], v[12:15]
	s_setprio 0
	s_waitcnt lgkmcnt(0)
	s_barrier
	ds_read_b128 v[194:197], v115 offset:49152
	ds_read_b128 v[156:159], v114 offset:32768
	ds_read_b128 v[198:201], v115 offset:51200
	ds_read_b128 v[202:205], v115 offset:53248
	ds_read_b128 v[206:209], v115 offset:55296
	ds_read_b128 v[166:169], v114 offset:34816
	ds_read_b128 v[170:173], v114 offset:36864
	ds_read_b128 v[174:177], v114 offset:38912
	s_setprio 1
	s_waitcnt lgkmcnt(3)
	v_mfma_f32_16x16x32_bf16 v[92:95], v[194:197], v[156:159], v[92:95]
	ds_read_b128 v[210:213], v117 offset:49152
	v_mfma_f32_16x16x32_bf16 v[88:91], v[198:201], v[156:159], v[88:91]
	ds_read_b128 v[178:181], v116 offset:32768
	v_mfma_f32_16x16x32_bf16 v[84:87], v[202:205], v[156:159], v[84:87]
	ds_read_b128 v[232:235], v117 offset:51200
	v_mfma_f32_16x16x32_bf16 v[0:3], v[206:209], v[156:159], v[0:3]
	ds_read_b128 v[236:239], v117 offset:53248
	s_waitcnt lgkmcnt(4)
	v_mfma_f32_16x16x32_bf16 v[28:31], v[194:197], v[166:169], v[28:31]
	ds_read_b128 v[240:243], v117 offset:55296
	v_mfma_f32_16x16x32_bf16 v[72:75], v[198:201], v[166:169], v[72:75]
	ds_read_b128 v[182:185], v116 offset:34816
	v_mfma_f32_16x16x32_bf16 v[68:71], v[202:205], v[166:169], v[68:71]
	ds_read_b128 v[186:189], v116 offset:36864
	v_mfma_f32_16x16x32_bf16 v[4:7], v[206:209], v[166:169], v[4:7]
	ds_read_b128 v[190:193], v116 offset:38912
	v_mfma_f32_16x16x32_bf16 v[32:35], v[194:197], v[170:173], v[32:35]
	v_mfma_f32_16x16x32_bf16 v[56:59], v[198:201], v[170:173], v[56:59]
	v_mfma_f32_16x16x32_bf16 v[52:55], v[202:205], v[170:173], v[52:55]
	v_mfma_f32_16x16x32_bf16 v[8:11], v[206:209], v[170:173], v[8:11]
	v_mfma_f32_16x16x32_bf16 v[16:19], v[194:197], v[174:177], v[16:19]
	v_mfma_f32_16x16x32_bf16 v[20:23], v[198:201], v[174:177], v[20:23]
	v_mfma_f32_16x16x32_bf16 v[24:27], v[202:205], v[174:177], v[24:27]
	v_mfma_f32_16x16x32_bf16 v[12:15], v[206:209], v[174:177], v[12:15]
	s_waitcnt lgkmcnt(3)
	v_mfma_f32_16x16x32_bf16 v[92:95], v[210:213], v[178:181], v[92:95]
	v_mfma_f32_16x16x32_bf16 v[88:91], v[232:235], v[178:181], v[88:91]
	v_mfma_f32_16x16x32_bf16 v[84:87], v[236:239], v[178:181], v[84:87]
	v_mfma_f32_16x16x32_bf16 v[0:3], v[240:243], v[178:181], v[0:3]
	s_waitcnt lgkmcnt(0)
	v_mfma_f32_16x16x32_bf16 v[28:31], v[210:213], v[182:185], v[28:31]
	v_mfma_f32_16x16x32_bf16 v[72:75], v[232:235], v[182:185], v[72:75]
	v_mfma_f32_16x16x32_bf16 v[68:71], v[236:239], v[182:185], v[68:71]
	v_mfma_f32_16x16x32_bf16 v[4:7], v[240:243], v[182:185], v[4:7]
	v_mfma_f32_16x16x32_bf16 v[32:35], v[210:213], v[186:189], v[32:35]
	v_mfma_f32_16x16x32_bf16 v[56:59], v[232:235], v[186:189], v[56:59]
	v_mfma_f32_16x16x32_bf16 v[52:55], v[236:239], v[186:189], v[52:55]
	v_mfma_f32_16x16x32_bf16 v[8:11], v[240:243], v[186:189], v[8:11]
	v_mfma_f32_16x16x32_bf16 v[16:19], v[210:213], v[190:193], v[16:19]
	v_mfma_f32_16x16x32_bf16 v[20:23], v[232:235], v[190:193], v[20:23]
	v_mfma_f32_16x16x32_bf16 v[24:27], v[236:239], v[190:193], v[24:27]
	v_mfma_f32_16x16x32_bf16 v[12:15], v[240:243], v[190:193], v[12:15]
	s_setprio 0
	s_nop 7
	v_add_u32_e32 v42, s4, v99
	v_or_b32_e32 v36, s5, v113
	v_mul_i32_i24_e32 v38, 0x1400, v42
	v_ashrrev_i32_e32 v39, 31, v38
	v_ashrrev_i32_e32 v37, 31, v36
	v_lshl_add_u64 v[38:39], s[28:29], 0, v[38:39]
	v_lshlrev_b64 v[36:37], 1, v[36:37]
	v_lshl_add_u64 v[38:39], v[38:39], 0, v[36:37]
	v_cvt_pk_bf16_f32 v0, v0, v1
	v_cvt_pk_bf16_f32 v1, v2, v3
	global_store_dwordx2 v[38:39], v[0:1], off offset:96
	v_add_u32_e32 v0, 16, v42
	v_cvt_pk_bf16_f32 v40, v92, v93
	v_cvt_pk_bf16_f32 v41, v94, v95
	v_mul_hi_i32_i24_e32 v1, 0x1400, v0
	v_mul_i32_i24_e32 v0, 0x1400, v0
	global_store_dwordx2 v[38:39], v[40:41], off
	v_cvt_pk_bf16_f32 v40, v88, v89
	v_cvt_pk_bf16_f32 v41, v90, v91
	v_lshl_add_u64 v[0:1], s[28:29], 0, v[0:1]
	global_store_dwordx2 v[38:39], v[40:41], off offset:32
	v_cvt_pk_bf16_f32 v40, v84, v85
	v_cvt_pk_bf16_f32 v41, v86, v87
	v_cvt_pk_bf16_f32 v2, v28, v29
	v_cvt_pk_bf16_f32 v3, v30, v31
	v_lshl_add_u64 v[0:1], v[0:1], 0, v[36:37]
	global_store_dwordx2 v[38:39], v[40:41], off offset:64
	global_store_dwordx2 v[0:1], v[2:3], off
	v_cvt_pk_bf16_f32 v2, v72, v73
	v_cvt_pk_bf16_f32 v3, v74, v75
	global_store_dwordx2 v[0:1], v[2:3], off offset:32
	v_cvt_pk_bf16_f32 v2, v68, v69
	v_cvt_pk_bf16_f32 v3, v70, v71
	global_store_dwordx2 v[0:1], v[2:3], off offset:64
	v_cvt_pk_bf16_f32 v2, v4, v5
	v_cvt_pk_bf16_f32 v3, v6, v7
	global_store_dwordx2 v[0:1], v[2:3], off offset:96
	v_add_u32_e32 v0, 32, v42
	v_mul_hi_i32_i24_e32 v1, 0x1400, v0
	v_mul_i32_i24_e32 v0, 0x1400, v0
	v_lshl_add_u64 v[0:1], s[28:29], 0, v[0:1]
	v_cvt_pk_bf16_f32 v2, v32, v33
	v_cvt_pk_bf16_f32 v3, v34, v35
	v_lshl_add_u64 v[0:1], v[0:1], 0, v[36:37]
	global_store_dwordx2 v[0:1], v[2:3], off
	v_cvt_pk_bf16_f32 v2, v56, v57
	v_cvt_pk_bf16_f32 v3, v58, v59
	global_store_dwordx2 v[0:1], v[2:3], off offset:32
	v_cvt_pk_bf16_f32 v2, v52, v53
	v_cvt_pk_bf16_f32 v3, v54, v55
	global_store_dwordx2 v[0:1], v[2:3], off offset:64
	v_cvt_pk_bf16_f32 v2, v8, v9
	v_cvt_pk_bf16_f32 v3, v10, v11
	global_store_dwordx2 v[0:1], v[2:3], off offset:96
	v_add_u32_e32 v0, 48, v42
	v_mul_hi_i32_i24_e32 v1, 0x1400, v0
	v_mul_i32_i24_e32 v0, 0x1400, v0
	v_lshl_add_u64 v[0:1], s[28:29], 0, v[0:1]
	v_cvt_pk_bf16_f32 v2, v16, v17
	v_cvt_pk_bf16_f32 v3, v18, v19
	v_lshl_add_u64 v[0:1], v[0:1], 0, v[36:37]
	global_store_dwordx2 v[0:1], v[2:3], off
	v_cvt_pk_bf16_f32 v2, v20, v21
	v_cvt_pk_bf16_f32 v3, v22, v23
	global_store_dwordx2 v[0:1], v[2:3], off offset:32
	v_cvt_pk_bf16_f32 v2, v24, v25
	v_cvt_pk_bf16_f32 v3, v26, v27
	global_store_dwordx2 v[0:1], v[2:3], off offset:64
	v_cvt_pk_bf16_f32 v2, v12, v13
	v_cvt_pk_bf16_f32 v3, v14, v15
	s_add_i32 s3, s3, 1
	s_mov_b64 s[0:1], 0
	global_store_dwordx2 v[0:1], v[2:3], off offset:96
	s_branch .LBB0_127

.Lgm_p5_loop:
	ds_read_b128 v[204:207], v132 offset:16384
	ds_read_b128 v[172:175], v133
	ds_read_b128 v[208:211], v132 offset:18432
	ds_read_b128 v[212:215], v132 offset:20480
	ds_read_b128 v[220:223], v132 offset:22528
	ds_read_b128 v[176:179], v133 offset:2048
	ds_read_b128 v[180:183], v133 offset:4096
	ds_read_b128 v[184:187], v133 offset:6144
	s_setprio 1
	s_waitcnt lgkmcnt(3)
	v_mfma_f32_16x16x32_bf16 v[92:95], v[204:207], v[172:175], v[92:95]
	ds_read_b128 v[224:227], v130 offset:16384
	v_mfma_f32_16x16x32_bf16 v[88:91], v[208:211], v[172:175], v[88:91]
	ds_read_b128 v[188:191], v131
	v_mfma_f32_16x16x32_bf16 v[84:87], v[212:215], v[172:175], v[84:87]
	ds_read_b128 v[230:233], v130 offset:18432
	v_mfma_f32_16x16x32_bf16 v[150:153], v[220:223], v[172:175], v[150:153]
	ds_read_b128 v[234:237], v130 offset:20480
	s_waitcnt lgkmcnt(4)
	v_mfma_f32_16x16x32_bf16 v[44:47], v[204:207], v[176:179], v[44:47]
	ds_read_b128 v[238:241], v130 offset:22528
	v_mfma_f32_16x16x32_bf16 v[40:43], v[208:211], v[176:179], v[40:43]
	ds_read_b128 v[192:195], v131 offset:2048
	v_mfma_f32_16x16x32_bf16 v[36:39], v[212:215], v[176:179], v[36:39]
	ds_read_b128 v[196:199], v131 offset:4096
	v_mfma_f32_16x16x32_bf16 v[32:35], v[220:223], v[176:179], v[32:35]
	ds_read_b128 v[200:203], v131 offset:6144
	v_mfma_f32_16x16x32_bf16 v[28:31], v[204:207], v[180:183], v[28:31]
	s_waitcnt vmcnt(8)
	ds_write_b128 v166, v[80:83] offset:32768
	v_mfma_f32_16x16x32_bf16 v[24:27], v[208:211], v[180:183], v[24:27]
	ds_write_b128 v166, v[138:141] offset:49152
	v_mfma_f32_16x16x32_bf16 v[20:23], v[212:215], v[180:183], v[20:23]
	ds_write_b128 v166, v[120:123] offset:36864
	v_mfma_f32_16x16x32_bf16 v[16:19], v[220:223], v[180:183], v[16:19]
	ds_write_b128 v166, v[142:145] offset:53248
	v_mfma_f32_16x16x32_bf16 v[12:15], v[204:207], v[184:187], v[12:15]
	ds_write_b128 v166, v[124:127] offset:40960
	v_mfma_f32_16x16x32_bf16 v[8:11], v[208:211], v[184:187], v[8:11]
	ds_write_b128 v166, v[146:149] offset:57344
	v_mfma_f32_16x16x32_bf16 v[4:7], v[212:215], v[184:187], v[4:7]
	ds_write_b128 v166, v[134:137] offset:45056
	v_mfma_f32_16x16x32_bf16 v[0:3], v[220:223], v[184:187], v[0:3]
	s_waitcnt lgkmcnt(8)
	ds_write_b128 v166, v[168:171] offset:61440
	v_mfma_f32_16x16x32_bf16 v[92:95], v[224:227], v[188:191], v[92:95]
	v_mfma_f32_16x16x32_bf16 v[88:91], v[230:233], v[188:191], v[88:91]
	v_mfma_f32_16x16x32_bf16 v[84:87], v[234:237], v[188:191], v[84:87]
	v_mfma_f32_16x16x32_bf16 v[150:153], v[238:241], v[188:191], v[150:153]
	s_waitcnt lgkmcnt(8)
	v_mfma_f32_16x16x32_bf16 v[44:47], v[224:227], v[192:195], v[44:47]
	s_waitcnt lgkmcnt(0)
	global_load_dwordx4 v[80:83], v116, s[100:101] offset:384
	v_mfma_f32_16x16x32_bf16 v[40:43], v[230:233], v[192:195], v[40:43]
	global_load_dwordx4 v[138:141], v118, s[98:99] offset:384
	v_mfma_f32_16x16x32_bf16 v[36:39], v[234:237], v[192:195], v[36:39]
	global_load_dwordx4 v[120:123], v117, s[100:101] offset:384
	v_mfma_f32_16x16x32_bf16 v[32:35], v[238:241], v[192:195], v[32:35]
	global_load_dwordx4 v[142:145], v119, s[98:99] offset:384
	v_mfma_f32_16x16x32_bf16 v[28:31], v[224:227], v[196:199], v[28:31]
	global_load_dwordx4 v[124:127], v97, s[100:101] offset:384
	v_mfma_f32_16x16x32_bf16 v[24:27], v[230:233], v[196:199], v[24:27]
	global_load_dwordx4 v[146:149], v103, s[98:99] offset:384
	v_mfma_f32_16x16x32_bf16 v[20:23], v[234:237], v[196:199], v[20:23]
	global_load_dwordx4 v[134:137], v101, s[100:101] offset:384
	v_mfma_f32_16x16x32_bf16 v[16:19], v[238:241], v[196:199], v[16:19]
	global_load_dwordx4 v[168:171], v105, s[98:99] offset:384
	v_mfma_f32_16x16x32_bf16 v[12:15], v[224:227], v[200:203], v[12:15]
	v_mfma_f32_16x16x32_bf16 v[8:11], v[230:233], v[200:203], v[8:11]
	v_mfma_f32_16x16x32_bf16 v[4:7], v[234:237], v[200:203], v[4:7]
	v_mfma_f32_16x16x32_bf16 v[0:3], v[238:241], v[200:203], v[0:3]
	s_setprio 0
	s_barrier
	ds_read_b128 v[204:207], v132 offset:49152
	ds_read_b128 v[172:175], v133 offset:32768
	ds_read_b128 v[208:211], v132 offset:51200
	ds_read_b128 v[212:215], v132 offset:53248
	ds_read_b128 v[220:223], v132 offset:55296
	ds_read_b128 v[176:179], v133 offset:34816
	ds_read_b128 v[180:183], v133 offset:36864
	ds_read_b128 v[184:187], v133 offset:38912
	s_setprio 1
	s_waitcnt lgkmcnt(3)
	v_mfma_f32_16x16x32_bf16 v[92:95], v[204:207], v[172:175], v[92:95]
	ds_read_b128 v[224:227], v130 offset:49152
	v_mfma_f32_16x16x32_bf16 v[88:91], v[208:211], v[172:175], v[88:91]
	ds_read_b128 v[188:191], v131 offset:32768
	v_mfma_f32_16x16x32_bf16 v[84:87], v[212:215], v[172:175], v[84:87]
	ds_read_b128 v[230:233], v130 offset:51200
	v_mfma_f32_16x16x32_bf16 v[150:153], v[220:223], v[172:175], v[150:153]
	ds_read_b128 v[234:237], v130 offset:53248
	s_waitcnt lgkmcnt(4)
	v_mfma_f32_16x16x32_bf16 v[44:47], v[204:207], v[176:179], v[44:47]
	ds_read_b128 v[238:241], v130 offset:55296
	v_mfma_f32_16x16x32_bf16 v[40:43], v[208:211], v[176:179], v[40:43]
	ds_read_b128 v[192:195], v131 offset:34816
	v_mfma_f32_16x16x32_bf16 v[36:39], v[212:215], v[176:179], v[36:39]
	ds_read_b128 v[196:199], v131 offset:36864
	v_mfma_f32_16x16x32_bf16 v[32:35], v[220:223], v[176:179], v[32:35]
	ds_read_b128 v[200:203], v131 offset:38912
	v_mfma_f32_16x16x32_bf16 v[28:31], v[204:207], v[180:183], v[28:31]
	s_waitcnt vmcnt(8)
	ds_write_b128 v166, v[48:51]
	v_mfma_f32_16x16x32_bf16 v[24:27], v[208:211], v[180:183], v[24:27]
	ds_write_b128 v166, v[64:67] offset:16384
	v_mfma_f32_16x16x32_bf16 v[20:23], v[212:215], v[180:183], v[20:23]
	ds_write_b128 v166, v[52:55] offset:4096
	v_mfma_f32_16x16x32_bf16 v[16:19], v[220:223], v[180:183], v[16:19]
	ds_write_b128 v166, v[68:71] offset:20480
	v_mfma_f32_16x16x32_bf16 v[12:15], v[204:207], v[184:187], v[12:15]
	ds_write_b128 v166, v[56:59] offset:8192
	v_mfma_f32_16x16x32_bf16 v[8:11], v[208:211], v[184:187], v[8:11]
	ds_write_b128 v166, v[72:75] offset:24576
	v_mfma_f32_16x16x32_bf16 v[4:7], v[212:215], v[184:187], v[4:7]
	ds_write_b128 v166, v[60:63] offset:12288
	v_mfma_f32_16x16x32_bf16 v[0:3], v[220:223], v[184:187], v[0:3]
	s_waitcnt lgkmcnt(8)
	ds_write_b128 v166, v[76:79] offset:28672
	v_mfma_f32_16x16x32_bf16 v[92:95], v[224:227], v[188:191], v[92:95]
	v_mfma_f32_16x16x32_bf16 v[88:91], v[230:233], v[188:191], v[88:91]
	v_mfma_f32_16x16x32_bf16 v[84:87], v[234:237], v[188:191], v[84:87]
	v_mfma_f32_16x16x32_bf16 v[150:153], v[238:241], v[188:191], v[150:153]
	s_waitcnt lgkmcnt(8)
	v_mfma_f32_16x16x32_bf16 v[44:47], v[224:227], v[192:195], v[44:47]
	s_waitcnt lgkmcnt(0)
	global_load_dwordx4 v[48:51], v116, s[100:101] offset:512
	v_mfma_f32_16x16x32_bf16 v[40:43], v[230:233], v[192:195], v[40:43]
	global_load_dwordx4 v[64:67], v118, s[98:99] offset:512
	v_mfma_f32_16x16x32_bf16 v[36:39], v[234:237], v[192:195], v[36:39]
	global_load_dwordx4 v[52:55], v117, s[100:101] offset:512
	v_mfma_f32_16x16x32_bf16 v[32:35], v[238:241], v[192:195], v[32:35]
	global_load_dwordx4 v[68:71], v119, s[98:99] offset:512
	v_mfma_f32_16x16x32_bf16 v[28:31], v[224:227], v[196:199], v[28:31]
	global_load_dwordx4 v[56:59], v97, s[100:101] offset:512
	v_mfma_f32_16x16x32_bf16 v[24:27], v[230:233], v[196:199], v[24:27]
	global_load_dwordx4 v[72:75], v103, s[98:99] offset:512
	v_mfma_f32_16x16x32_bf16 v[20:23], v[234:237], v[196:199], v[20:23]
	global_load_dwordx4 v[60:63], v101, s[100:101] offset:512
	v_mfma_f32_16x16x32_bf16 v[16:19], v[238:241], v[196:199], v[16:19]
	global_load_dwordx4 v[76:79], v105, s[98:99] offset:512
	v_mfma_f32_16x16x32_bf16 v[12:15], v[224:227], v[200:203], v[12:15]
	v_mfma_f32_16x16x32_bf16 v[8:11], v[230:233], v[200:203], v[8:11]
	v_mfma_f32_16x16x32_bf16 v[4:7], v[234:237], v[200:203], v[4:7]
	v_mfma_f32_16x16x32_bf16 v[0:3], v[238:241], v[200:203], v[0:3]
	s_setprio 0
	s_barrier
	s_add_u32 s100, s100, 0x100
	s_addc_u32 s101, s101, 0
	s_add_u32 s98, s98, 0x100
	s_addc_u32 s99, s99, 0
	s_sub_u32 s94, s94, 1
	s_cmp_lg_u32 s94, 0
	s_cbranch_scc1 .Lgm_p5_loop
	ds_read_b128 v[204:207], v132 offset:16384
	ds_read_b128 v[172:175], v133
	ds_read_b128 v[208:211], v132 offset:18432
	ds_read_b128 v[212:215], v132 offset:20480
	ds_read_b128 v[220:223], v132 offset:22528
	ds_read_b128 v[176:179], v133 offset:2048
	ds_read_b128 v[180:183], v133 offset:4096
	ds_read_b128 v[184:187], v133 offset:6144
	s_setprio 1
	s_waitcnt lgkmcnt(3)
	v_mfma_f32_16x16x32_bf16 v[92:95], v[204:207], v[172:175], v[92:95]
	ds_read_b128 v[224:227], v130 offset:16384
	v_mfma_f32_16x16x32_bf16 v[88:91], v[208:211], v[172:175], v[88:91]
	ds_read_b128 v[188:191], v131
	v_mfma_f32_16x16x32_bf16 v[84:87], v[212:215], v[172:175], v[84:87]
	ds_read_b128 v[230:233], v130 offset:18432
	v_mfma_f32_16x16x32_bf16 v[150:153], v[220:223], v[172:175], v[150:153]
	ds_read_b128 v[234:237], v130 offset:20480
	s_waitcnt lgkmcnt(4)
	v_mfma_f32_16x16x32_bf16 v[44:47], v[204:207], v[176:179], v[44:47]
	ds_read_b128 v[238:241], v130 offset:22528
	v_mfma_f32_16x16x32_bf16 v[40:43], v[208:211], v[176:179], v[40:43]
	ds_read_b128 v[192:195], v131 offset:2048
	v_mfma_f32_16x16x32_bf16 v[36:39], v[212:215], v[176:179], v[36:39]
	ds_read_b128 v[196:199], v131 offset:4096
	v_mfma_f32_16x16x32_bf16 v[32:35], v[220:223], v[176:179], v[32:35]
	ds_read_b128 v[200:203], v131 offset:6144
	v_mfma_f32_16x16x32_bf16 v[28:31], v[204:207], v[180:183], v[28:31]
	s_waitcnt vmcnt(8)
	ds_write_b128 v166, v[80:83] offset:32768
	v_mfma_f32_16x16x32_bf16 v[24:27], v[208:211], v[180:183], v[24:27]
	ds_write_b128 v166, v[138:141] offset:49152
	v_mfma_f32_16x16x32_bf16 v[20:23], v[212:215], v[180:183], v[20:23]
	ds_write_b128 v166, v[120:123] offset:36864
	v_mfma_f32_16x16x32_bf16 v[16:19], v[220:223], v[180:183], v[16:19]
	ds_write_b128 v166, v[142:145] offset:53248
	v_mfma_f32_16x16x32_bf16 v[12:15], v[204:207], v[184:187], v[12:15]
	ds_write_b128 v166, v[124:127] offset:40960
	v_mfma_f32_16x16x32_bf16 v[8:11], v[208:211], v[184:187], v[8:11]
	ds_write_b128 v166, v[146:149] offset:57344
	v_mfma_f32_16x16x32_bf16 v[4:7], v[212:215], v[184:187], v[4:7]
	ds_write_b128 v166, v[134:137] offset:45056
	v_mfma_f32_16x16x32_bf16 v[0:3], v[220:223], v[184:187], v[0:3]
	s_waitcnt lgkmcnt(8)
	ds_write_b128 v166, v[168:171] offset:61440
	v_mfma_f32_16x16x32_bf16 v[92:95], v[224:227], v[188:191], v[92:95]
	v_mfma_f32_16x16x32_bf16 v[88:91], v[230:233], v[188:191], v[88:91]
	v_mfma_f32_16x16x32_bf16 v[84:87], v[234:237], v[188:191], v[84:87]
	v_mfma_f32_16x16x32_bf16 v[150:153], v[238:241], v[188:191], v[150:153]
	s_waitcnt lgkmcnt(8)
	v_mfma_f32_16x16x32_bf16 v[44:47], v[224:227], v[192:195], v[44:47]
	s_waitcnt lgkmcnt(0)
	global_load_dwordx4 v[80:83], v116, s[100:101] offset:384
	v_mfma_f32_16x16x32_bf16 v[40:43], v[230:233], v[192:195], v[40:43]
	global_load_dwordx4 v[138:141], v118, s[98:99] offset:384
	v_mfma_f32_16x16x32_bf16 v[36:39], v[234:237], v[192:195], v[36:39]
	global_load_dwordx4 v[120:123], v117, s[100:101] offset:384
	v_mfma_f32_16x16x32_bf16 v[32:35], v[238:241], v[192:195], v[32:35]
	global_load_dwordx4 v[142:145], v119, s[98:99] offset:384
	v_mfma_f32_16x16x32_bf16 v[28:31], v[224:227], v[196:199], v[28:31]
	global_load_dwordx4 v[124:127], v97, s[100:101] offset:384
	v_mfma_f32_16x16x32_bf16 v[24:27], v[230:233], v[196:199], v[24:27]
	global_load_dwordx4 v[146:149], v103, s[98:99] offset:384
	v_mfma_f32_16x16x32_bf16 v[20:23], v[234:237], v[196:199], v[20:23]
	global_load_dwordx4 v[134:137], v101, s[100:101] offset:384
	v_mfma_f32_16x16x32_bf16 v[16:19], v[238:241], v[196:199], v[16:19]
	global_load_dwordx4 v[168:171], v105, s[98:99] offset:384
	v_mfma_f32_16x16x32_bf16 v[12:15], v[224:227], v[200:203], v[12:15]
	v_mfma_f32_16x16x32_bf16 v[8:11], v[230:233], v[200:203], v[8:11]
	v_mfma_f32_16x16x32_bf16 v[4:7], v[234:237], v[200:203], v[4:7]
	v_mfma_f32_16x16x32_bf16 v[0:3], v[238:241], v[200:203], v[0:3]
	s_setprio 0
	s_barrier
	ds_read_b128 v[204:207], v132 offset:49152
	ds_read_b128 v[172:175], v133 offset:32768
	ds_read_b128 v[208:211], v132 offset:51200
	ds_read_b128 v[212:215], v132 offset:53248
	ds_read_b128 v[220:223], v132 offset:55296
	ds_read_b128 v[176:179], v133 offset:34816
	ds_read_b128 v[180:183], v133 offset:36864
	ds_read_b128 v[184:187], v133 offset:38912
	s_setprio 1
	s_waitcnt lgkmcnt(3)
	v_mfma_f32_16x16x32_bf16 v[92:95], v[204:207], v[172:175], v[92:95]
	ds_read_b128 v[224:227], v130 offset:49152
	v_mfma_f32_16x16x32_bf16 v[88:91], v[208:211], v[172:175], v[88:91]
	ds_read_b128 v[188:191], v131 offset:32768
	v_mfma_f32_16x16x32_bf16 v[84:87], v[212:215], v[172:175], v[84:87]
	ds_read_b128 v[230:233], v130 offset:51200
	v_mfma_f32_16x16x32_bf16 v[150:153], v[220:223], v[172:175], v[150:153]
	ds_read_b128 v[234:237], v130 offset:53248
	s_waitcnt lgkmcnt(4)
	v_mfma_f32_16x16x32_bf16 v[44:47], v[204:207], v[176:179], v[44:47]
	ds_read_b128 v[238:241], v130 offset:55296
	v_mfma_f32_16x16x32_bf16 v[40:43], v[208:211], v[176:179], v[40:43]
	ds_read_b128 v[192:195], v131 offset:34816
	v_mfma_f32_16x16x32_bf16 v[36:39], v[212:215], v[176:179], v[36:39]
	ds_read_b128 v[196:199], v131 offset:36864
	v_mfma_f32_16x16x32_bf16 v[32:35], v[220:223], v[176:179], v[32:35]
	ds_read_b128 v[200:203], v131 offset:38912
	v_mfma_f32_16x16x32_bf16 v[28:31], v[204:207], v[180:183], v[28:31]
	s_waitcnt vmcnt(8)
	ds_write_b128 v166, v[48:51]
	v_mfma_f32_16x16x32_bf16 v[24:27], v[208:211], v[180:183], v[24:27]
	ds_write_b128 v166, v[64:67] offset:16384
	v_mfma_f32_16x16x32_bf16 v[20:23], v[212:215], v[180:183], v[20:23]
	ds_write_b128 v166, v[52:55] offset:4096
	v_mfma_f32_16x16x32_bf16 v[16:19], v[220:223], v[180:183], v[16:19]
	ds_write_b128 v166, v[68:71] offset:20480
	v_mfma_f32_16x16x32_bf16 v[12:15], v[204:207], v[184:187], v[12:15]
	ds_write_b128 v166, v[56:59] offset:8192
	v_mfma_f32_16x16x32_bf16 v[8:11], v[208:211], v[184:187], v[8:11]
	ds_write_b128 v166, v[72:75] offset:24576
	v_mfma_f32_16x16x32_bf16 v[4:7], v[212:215], v[184:187], v[4:7]
	ds_write_b128 v166, v[60:63] offset:12288
	v_mfma_f32_16x16x32_bf16 v[0:3], v[220:223], v[184:187], v[0:3]
	s_waitcnt lgkmcnt(8)
	ds_write_b128 v166, v[76:79] offset:28672
	v_mfma_f32_16x16x32_bf16 v[92:95], v[224:227], v[188:191], v[92:95]
	v_mfma_f32_16x16x32_bf16 v[88:91], v[230:233], v[188:191], v[88:91]
	v_mfma_f32_16x16x32_bf16 v[84:87], v[234:237], v[188:191], v[84:87]
	v_mfma_f32_16x16x32_bf16 v[150:153], v[238:241], v[188:191], v[150:153]
	s_waitcnt lgkmcnt(8)
	v_mfma_f32_16x16x32_bf16 v[44:47], v[224:227], v[192:195], v[44:47]
	v_mfma_f32_16x16x32_bf16 v[40:43], v[230:233], v[192:195], v[40:43]
	v_mfma_f32_16x16x32_bf16 v[36:39], v[234:237], v[192:195], v[36:39]
	v_mfma_f32_16x16x32_bf16 v[32:35], v[238:241], v[192:195], v[32:35]
	v_mfma_f32_16x16x32_bf16 v[28:31], v[224:227], v[196:199], v[28:31]
	v_mfma_f32_16x16x32_bf16 v[24:27], v[230:233], v[196:199], v[24:27]
	v_mfma_f32_16x16x32_bf16 v[20:23], v[234:237], v[196:199], v[20:23]
	v_mfma_f32_16x16x32_bf16 v[16:19], v[238:241], v[196:199], v[16:19]
	v_mfma_f32_16x16x32_bf16 v[12:15], v[224:227], v[200:203], v[12:15]
	v_mfma_f32_16x16x32_bf16 v[8:11], v[230:233], v[200:203], v[8:11]
	v_mfma_f32_16x16x32_bf16 v[4:7], v[234:237], v[200:203], v[4:7]
	v_mfma_f32_16x16x32_bf16 v[0:3], v[238:241], v[200:203], v[0:3]
	s_setprio 0
	s_waitcnt lgkmcnt(0)
	s_barrier
	ds_read_b128 v[204:207], v132 offset:16384
	ds_read_b128 v[172:175], v133
	ds_read_b128 v[208:211], v132 offset:18432
	ds_read_b128 v[212:215], v132 offset:20480
	ds_read_b128 v[220:223], v132 offset:22528
	ds_read_b128 v[176:179], v133 offset:2048
	ds_read_b128 v[180:183], v133 offset:4096
	ds_read_b128 v[184:187], v133 offset:6144
	s_setprio 1
	s_waitcnt lgkmcnt(3)
	v_mfma_f32_16x16x32_bf16 v[92:95], v[204:207], v[172:175], v[92:95]
	ds_read_b128 v[224:227], v130 offset:16384
	v_mfma_f32_16x16x32_bf16 v[88:91], v[208:211], v[172:175], v[88:91]
	ds_read_b128 v[188:191], v131
	v_mfma_f32_16x16x32_bf16 v[84:87], v[212:215], v[172:175], v[84:87]
	ds_read_b128 v[230:233], v130 offset:18432
	v_mfma_f32_16x16x32_bf16 v[150:153], v[220:223], v[172:175], v[150:153]
	ds_read_b128 v[234:237], v130 offset:20480
	s_waitcnt lgkmcnt(4)
	v_mfma_f32_16x16x32_bf16 v[44:47], v[204:207], v[176:179], v[44:47]
	ds_read_b128 v[238:241], v130 offset:22528
	v_mfma_f32_16x16x32_bf16 v[40:43], v[208:211], v[176:179], v[40:43]
	ds_read_b128 v[192:195], v131 offset:2048
	v_mfma_f32_16x16x32_bf16 v[36:39], v[212:215], v[176:179], v[36:39]
	ds_read_b128 v[196:199], v131 offset:4096
	v_mfma_f32_16x16x32_bf16 v[32:35], v[220:223], v[176:179], v[32:35]
	ds_read_b128 v[200:203], v131 offset:6144
	v_mfma_f32_16x16x32_bf16 v[28:31], v[204:207], v[180:183], v[28:31]
	s_waitcnt vmcnt(0)
	ds_write_b128 v166, v[80:83] offset:32768
	v_mfma_f32_16x16x32_bf16 v[24:27], v[208:211], v[180:183], v[24:27]
	ds_write_b128 v166, v[138:141] offset:49152
	v_mfma_f32_16x16x32_bf16 v[20:23], v[212:215], v[180:183], v[20:23]
	ds_write_b128 v166, v[120:123] offset:36864
	v_mfma_f32_16x16x32_bf16 v[16:19], v[220:223], v[180:183], v[16:19]
	ds_write_b128 v166, v[142:145] offset:53248
	v_mfma_f32_16x16x32_bf16 v[12:15], v[204:207], v[184:187], v[12:15]
	ds_write_b128 v166, v[124:127] offset:40960
	v_mfma_f32_16x16x32_bf16 v[8:11], v[208:211], v[184:187], v[8:11]
	ds_write_b128 v166, v[146:149] offset:57344
	v_mfma_f32_16x16x32_bf16 v[4:7], v[212:215], v[184:187], v[4:7]
	ds_write_b128 v166, v[134:137] offset:45056
	v_mfma_f32_16x16x32_bf16 v[0:3], v[220:223], v[184:187], v[0:3]
	s_waitcnt lgkmcnt(8)
	ds_write_b128 v166, v[168:171] offset:61440
	v_mfma_f32_16x16x32_bf16 v[92:95], v[224:227], v[188:191], v[92:95]
	v_mfma_f32_16x16x32_bf16 v[88:91], v[230:233], v[188:191], v[88:91]
	v_mfma_f32_16x16x32_bf16 v[84:87], v[234:237], v[188:191], v[84:87]
	v_mfma_f32_16x16x32_bf16 v[150:153], v[238:241], v[188:191], v[150:153]
	s_waitcnt lgkmcnt(8)
	v_mfma_f32_16x16x32_bf16 v[44:47], v[224:227], v[192:195], v[44:47]
	v_mfma_f32_16x16x32_bf16 v[40:43], v[230:233], v[192:195], v[40:43]
	v_mfma_f32_16x16x32_bf16 v[36:39], v[234:237], v[192:195], v[36:39]
	v_mfma_f32_16x16x32_bf16 v[32:35], v[238:241], v[192:195], v[32:35]
	v_mfma_f32_16x16x32_bf16 v[28:31], v[224:227], v[196:199], v[28:31]
	v_mfma_f32_16x16x32_bf16 v[24:27], v[230:233], v[196:199], v[24:27]
	v_mfma_f32_16x16x32_bf16 v[20:23], v[234:237], v[196:199], v[20:23]
	v_mfma_f32_16x16x32_bf16 v[16:19], v[238:241], v[196:199], v[16:19]
	v_mfma_f32_16x16x32_bf16 v[12:15], v[224:227], v[200:203], v[12:15]
	v_mfma_f32_16x16x32_bf16 v[8:11], v[230:233], v[200:203], v[8:11]
	v_mfma_f32_16x16x32_bf16 v[4:7], v[234:237], v[200:203], v[4:7]
	v_mfma_f32_16x16x32_bf16 v[0:3], v[238:241], v[200:203], v[0:3]
	s_setprio 0
	s_waitcnt lgkmcnt(0)
	s_barrier
	ds_read_b128 v[204:207], v132 offset:49152
	ds_read_b128 v[172:175], v133 offset:32768
	ds_read_b128 v[208:211], v132 offset:51200
	ds_read_b128 v[212:215], v132 offset:53248
	ds_read_b128 v[220:223], v132 offset:55296
	ds_read_b128 v[176:179], v133 offset:34816
	ds_read_b128 v[180:183], v133 offset:36864
	ds_read_b128 v[184:187], v133 offset:38912
	s_setprio 1
	s_waitcnt lgkmcnt(3)
	v_mfma_f32_16x16x32_bf16 v[92:95], v[204:207], v[172:175], v[92:95]
	ds_read_b128 v[224:227], v130 offset:49152
	v_mfma_f32_16x16x32_bf16 v[88:91], v[208:211], v[172:175], v[88:91]
	ds_read_b128 v[188:191], v131 offset:32768
	v_mfma_f32_16x16x32_bf16 v[84:87], v[212:215], v[172:175], v[84:87]
	ds_read_b128 v[230:233], v130 offset:51200
	v_mfma_f32_16x16x32_bf16 v[150:153], v[220:223], v[172:175], v[150:153]
	ds_read_b128 v[234:237], v130 offset:53248
	s_waitcnt lgkmcnt(4)
	v_mfma_f32_16x16x32_bf16 v[44:47], v[204:207], v[176:179], v[44:47]
	ds_read_b128 v[238:241], v130 offset:55296
	v_mfma_f32_16x16x32_bf16 v[40:43], v[208:211], v[176:179], v[40:43]
	ds_read_b128 v[192:195], v131 offset:34816
	v_mfma_f32_16x16x32_bf16 v[36:39], v[212:215], v[176:179], v[36:39]
	ds_read_b128 v[196:199], v131 offset:36864
	v_mfma_f32_16x16x32_bf16 v[32:35], v[220:223], v[176:179], v[32:35]
	ds_read_b128 v[200:203], v131 offset:38912
	v_mfma_f32_16x16x32_bf16 v[28:31], v[204:207], v[180:183], v[28:31]
	v_mfma_f32_16x16x32_bf16 v[24:27], v[208:211], v[180:183], v[24:27]
	v_mfma_f32_16x16x32_bf16 v[20:23], v[212:215], v[180:183], v[20:23]
	v_mfma_f32_16x16x32_bf16 v[16:19], v[220:223], v[180:183], v[16:19]
	v_mfma_f32_16x16x32_bf16 v[12:15], v[204:207], v[184:187], v[12:15]
	v_mfma_f32_16x16x32_bf16 v[8:11], v[208:211], v[184:187], v[8:11]
	v_mfma_f32_16x16x32_bf16 v[4:7], v[212:215], v[184:187], v[4:7]
	v_mfma_f32_16x16x32_bf16 v[0:3], v[220:223], v[184:187], v[0:3]
	s_waitcnt lgkmcnt(3)
	v_mfma_f32_16x16x32_bf16 v[92:95], v[224:227], v[188:191], v[92:95]
	v_mfma_f32_16x16x32_bf16 v[88:91], v[230:233], v[188:191], v[88:91]
	v_mfma_f32_16x16x32_bf16 v[84:87], v[234:237], v[188:191], v[84:87]
	v_mfma_f32_16x16x32_bf16 v[150:153], v[238:241], v[188:191], v[150:153]
	s_waitcnt lgkmcnt(0)
	v_mfma_f32_16x16x32_bf16 v[44:47], v[224:227], v[192:195], v[44:47]
	v_mfma_f32_16x16x32_bf16 v[40:43], v[230:233], v[192:195], v[40:43]
	v_mfma_f32_16x16x32_bf16 v[36:39], v[234:237], v[192:195], v[36:39]
	v_mfma_f32_16x16x32_bf16 v[32:35], v[238:241], v[192:195], v[32:35]
	v_mfma_f32_16x16x32_bf16 v[28:31], v[224:227], v[196:199], v[28:31]
	v_mfma_f32_16x16x32_bf16 v[24:27], v[230:233], v[196:199], v[24:27]
	v_mfma_f32_16x16x32_bf16 v[20:23], v[234:237], v[196:199], v[20:23]
	v_mfma_f32_16x16x32_bf16 v[16:19], v[238:241], v[196:199], v[16:19]
	v_mfma_f32_16x16x32_bf16 v[12:15], v[224:227], v[200:203], v[12:15]
	v_mfma_f32_16x16x32_bf16 v[8:11], v[230:233], v[200:203], v[8:11]
	v_mfma_f32_16x16x32_bf16 v[4:7], v[234:237], v[200:203], v[4:7]
	v_mfma_f32_16x16x32_bf16 v[0:3], v[238:241], v[200:203], v[0:3]
	s_setprio 0
	s_nop 7
	v_readlane_b32 s44, v252, 8
	v_readlane_b32 s45, v252, 9
	v_add_u32_e32 v50, s5, v167
	v_readlane_b32 s46, v252, 10
	v_readlane_b32 s47, v252, 11
	s_mov_b64 s[12:13], s[44:45]
	v_add_u32_e32 v48, 0xffffc000, v50
	v_ashrrev_i32_e32 v51, 31, v50
	v_cmp_gt_i32_e32 vcc, s18, v50
	s_mov_b64 s[14:15], s[46:47]
	v_mov_b32_e32 v76, s15
	v_cndmask_b32_e32 v49, 0, v51, vcc
	v_cndmask_b32_e32 v48, v48, v50, vcc
	v_mov_b32_e32 v77, s13
	v_mov_b32_e32 v78, s14
	v_mov_b32_e32 v79, s12
	s_ashr_i32 s5, s4, 31
	v_cndmask_b32_e32 v53, v76, v77, vcc
	v_cndmask_b32_e32 v52, v78, v79, vcc
	v_lshlrev_b64 v[48:49], 12, v[48:49]
	v_lshl_add_u64 v[48:49], v[52:53], 0, v[48:49]
	s_lshl_b64 s[4:5], s[4:5], 2
	v_lshl_add_u64 v[48:49], v[48:49], 0, s[4:5]
	v_lshlrev_b32_e32 v110, 2, v102
	v_lshl_add_u64 v[52:53], v[48:49], 0, v[110:111]
	v_lshlrev_b32_e32 v48, 2, v104
	v_mov_b32_e32 v49, v111
	v_lshl_add_u64 v[64:65], v[52:53], 0, v[48:49]
	global_load_dwordx4 v[52:55], v[64:65], off
	global_load_dwordx4 v[56:59], v[64:65], off offset:64
	global_load_dwordx4 v[60:63], v[64:65], off offset:128
	s_nop 0
	global_load_dwordx4 v[64:67], v[64:65], off offset:192
	v_readlane_b32 s48, v252, 12
	v_readlane_b32 s49, v252, 13
	v_readlane_b32 s50, v252, 14
	v_readlane_b32 s51, v252, 15
	v_readlane_b32 s52, v252, 16
	v_readlane_b32 s53, v252, 17
	v_readlane_b32 s54, v252, 18
	v_readlane_b32 s55, v252, 19
	v_readlane_b32 s56, v252, 20
	v_readlane_b32 s57, v252, 21
	v_readlane_b32 s58, v252, 22
	v_readlane_b32 s59, v252, 23
	v_or_b32_e32 v68, 16, v50
	v_add_u32_e32 v72, 0xffffc010, v50
	v_ashrrev_i32_e32 v69, 31, v68
	v_readlane_b32 s44, v251, 40
	v_cmp_gt_i32_e32 vcc, s18, v68
	v_lshlrev_b64 v[70:71], 12, v[50:51]
	v_readlane_b32 s52, v251, 48
	v_readlane_b32 s53, v251, 49
	v_cndmask_b32_e32 v73, 0, v69, vcc
	v_cndmask_b32_e32 v72, v72, v68, vcc
	v_lshl_add_u64 v[70:71], s[52:53], 0, v[70:71]
	v_cndmask_b32_e32 v75, v76, v77, vcc
	v_cndmask_b32_e32 v74, v78, v79, vcc
	v_lshlrev_b64 v[72:73], 12, v[72:73]
	v_lshl_add_u64 v[70:71], v[70:71], 0, s[4:5]
	v_lshl_add_u64 v[72:73], v[74:75], 0, v[72:73]
	v_lshl_add_u64 v[70:71], v[70:71], 0, v[110:111]
	v_lshl_add_u64 v[72:73], v[72:73], 0, s[4:5]
	v_lshl_add_u64 v[70:71], v[70:71], 0, v[48:49]
	v_lshl_add_u64 v[72:73], v[72:73], 0, v[110:111]
	v_lshl_add_u64 v[72:73], v[72:73], 0, v[48:49]
	v_add_u32_e32 v51, 0xffffc020, v50
	v_lshlrev_b64 v[68:69], 12, v[68:69]
	v_lshl_add_u64 v[68:69], s[52:53], 0, v[68:69]
	v_lshl_add_u64 v[68:69], v[68:69], 0, s[4:5]
	v_lshl_add_u64 v[68:69], v[68:69], 0, v[110:111]
	v_lshl_add_u64 v[68:69], v[68:69], 0, v[48:49]
	s_mov_b32 s8, 0
	v_readlane_b32 s45, v251, 41
	v_readlane_b32 s46, v251, 42
	v_readlane_b32 s47, v251, 43
	v_readlane_b32 s48, v251, 44
	v_readlane_b32 s49, v251, 45
	v_readlane_b32 s50, v251, 46
	v_readlane_b32 s51, v251, 47
	v_readlane_b32 s54, v251, 50
	v_readlane_b32 s55, v251, 51
	v_readlane_b32 s56, v251, 52
	v_readlane_b32 s57, v251, 53
	v_readlane_b32 s58, v251, 54
	v_readlane_b32 s59, v251, 55
	s_waitcnt vmcnt(3)
	v_pk_add_f32 v[52:53], v[92:93], v[52:53]
	v_pk_add_f32 v[54:55], v[94:95], v[54:55]
	s_waitcnt vmcnt(2)
	v_pk_add_f32 v[56:57], v[88:89], v[56:57]
	v_pk_add_f32 v[58:59], v[90:91], v[58:59]
	s_waitcnt vmcnt(1)
	v_pk_add_f32 v[60:61], v[84:85], v[60:61]
	v_pk_add_f32 v[62:63], v[86:87], v[62:63]
	s_waitcnt vmcnt(0)
	v_pk_add_f32 v[64:65], v[150:151], v[64:65]
	v_pk_add_f32 v[66:67], v[152:153], v[66:67]
	global_store_dwordx4 v[70:71], v[52:55], off
	global_store_dwordx4 v[70:71], v[56:59], off offset:64
	global_store_dwordx4 v[70:71], v[60:63], off offset:128
	global_store_dwordx4 v[70:71], v[64:67], off offset:192
	global_load_dwordx4 v[52:55], v[72:73], off
	s_nop 0
	global_load_dwordx4 v[56:59], v[72:73], off offset:64
	global_load_dwordx4 v[60:63], v[72:73], off offset:128
	global_load_dwordx4 v[64:67], v[72:73], off offset:192
	v_or_b32_e32 v70, 32, v50
	v_ashrrev_i32_e32 v71, 31, v70
	v_cmp_gt_i32_e32 vcc, s18, v70
	s_waitcnt vmcnt(3)
	v_pk_add_f32 v[44:45], v[44:45], v[52:53]
	v_cndmask_b32_e32 v73, 0, v71, vcc
	v_cndmask_b32_e32 v72, v51, v70, vcc
	v_cndmask_b32_e32 v75, v76, v77, vcc
	v_cndmask_b32_e32 v74, v78, v79, vcc
	v_lshlrev_b64 v[72:73], 12, v[72:73]
	v_lshl_add_u64 v[72:73], v[74:75], 0, v[72:73]
	v_lshl_add_u64 v[72:73], v[72:73], 0, s[4:5]
	v_lshl_add_u64 v[72:73], v[72:73], 0, v[110:111]
	v_pk_add_f32 v[46:47], v[46:47], v[54:55]
	v_lshl_add_u64 v[72:73], v[72:73], 0, v[48:49]
	s_waitcnt vmcnt(2)
	v_pk_add_f32 v[40:41], v[40:41], v[56:57]
	v_pk_add_f32 v[42:43], v[42:43], v[58:59]
	s_waitcnt vmcnt(1)
	v_pk_add_f32 v[36:37], v[36:37], v[60:61]
	v_pk_add_f32 v[38:39], v[38:39], v[62:63]
	s_waitcnt vmcnt(0)
	v_pk_add_f32 v[32:33], v[32:33], v[64:65]
	v_pk_add_f32 v[34:35], v[34:35], v[66:67]
	global_store_dwordx4 v[68:69], v[44:47], off
	global_store_dwordx4 v[68:69], v[40:43], off offset:64
	global_store_dwordx4 v[68:69], v[36:39], off offset:128
	global_store_dwordx4 v[68:69], v[32:35], off offset:192
	global_load_dwordx4 v[32:35], v[72:73], off
	s_nop 0
	global_load_dwordx4 v[36:39], v[72:73], off offset:64
	global_load_dwordx4 v[40:43], v[72:73], off offset:128
	global_load_dwordx4 v[44:47], v[72:73], off offset:192
	v_or_b32_e32 v52, 48, v50
	v_add_u32_e32 v54, 0xffffc030, v50
	v_ashrrev_i32_e32 v53, 31, v52
	v_cmp_gt_i32_e32 vcc, s18, v52
	v_lshlrev_b64 v[50:51], 12, v[70:71]
	v_lshl_add_u64 v[50:51], s[52:53], 0, v[50:51]
	v_cndmask_b32_e32 v55, 0, v53, vcc
	v_cndmask_b32_e32 v54, v54, v52, vcc
	v_cndmask_b32_e32 v57, v76, v77, vcc
	v_cndmask_b32_e32 v56, v78, v79, vcc
	v_lshlrev_b64 v[54:55], 12, v[54:55]
	v_lshl_add_u64 v[50:51], v[50:51], 0, s[4:5]
	v_lshl_add_u64 v[54:55], v[56:57], 0, v[54:55]
	v_lshl_add_u64 v[50:51], v[50:51], 0, v[110:111]
	v_lshl_add_u64 v[54:55], v[54:55], 0, s[4:5]
	v_lshl_add_u64 v[50:51], v[50:51], 0, v[48:49]
	v_lshl_add_u64 v[54:55], v[54:55], 0, v[110:111]
	v_lshl_add_u64 v[54:55], v[54:55], 0, v[48:49]
	s_waitcnt vmcnt(3)
	v_pk_add_f32 v[28:29], v[28:29], v[32:33]
	v_pk_add_f32 v[30:31], v[30:31], v[34:35]
	s_waitcnt vmcnt(2)
	v_pk_add_f32 v[24:25], v[24:25], v[36:37]
	v_pk_add_f32 v[26:27], v[26:27], v[38:39]
	s_waitcnt vmcnt(1)
	v_pk_add_f32 v[20:21], v[20:21], v[40:41]
	v_pk_add_f32 v[22:23], v[22:23], v[42:43]
	s_waitcnt vmcnt(0)
	v_pk_add_f32 v[16:17], v[16:17], v[44:45]
	v_pk_add_f32 v[18:19], v[18:19], v[46:47]
	global_store_dwordx4 v[50:51], v[28:31], off
	global_store_dwordx4 v[50:51], v[24:27], off offset:64
	global_store_dwordx4 v[50:51], v[20:23], off offset:128
	global_store_dwordx4 v[50:51], v[16:19], off offset:192
	global_load_dwordx4 v[16:19], v[54:55], off
	s_nop 0
	global_load_dwordx4 v[20:23], v[54:55], off offset:64
	global_load_dwordx4 v[24:27], v[54:55], off offset:128
	global_load_dwordx4 v[28:31], v[54:55], off offset:192
	v_lshlrev_b64 v[32:33], 12, v[52:53]
	v_lshl_add_u64 v[32:33], s[52:53], 0, v[32:33]
	v_lshl_add_u64 v[32:33], v[32:33], 0, s[4:5]
	v_lshl_add_u64 v[32:33], v[32:33], 0, v[110:111]
	v_lshl_add_u64 v[32:33], v[32:33], 0, v[48:49]
	s_waitcnt vmcnt(3)
	v_pk_add_f32 v[12:13], v[12:13], v[16:17]
	v_pk_add_f32 v[14:15], v[14:15], v[18:19]
	s_waitcnt vmcnt(2)
	v_pk_add_f32 v[8:9], v[8:9], v[20:21]
	v_pk_add_f32 v[10:11], v[10:11], v[22:23]
	s_waitcnt vmcnt(1)
	v_pk_add_f32 v[4:5], v[4:5], v[24:25]
	v_pk_add_f32 v[6:7], v[6:7], v[26:27]
	s_waitcnt vmcnt(0)
	v_pk_add_f32 v[0:1], v[0:1], v[28:29]
	v_pk_add_f32 v[2:3], v[2:3], v[30:31]
	global_store_dwordx4 v[32:33], v[12:15], off
	global_store_dwordx4 v[32:33], v[8:11], off offset:64
	global_store_dwordx4 v[32:33], v[4:7], off offset:128
	global_store_dwordx4 v[32:33], v[0:3], off offset:192
	s_mov_b64 s[4:5], -1
	s_cmp_gt_i32 s8, 3
	s_mov_b64 s[6:7], -1
	s_cbranch_scc1 .LBB0_681

.Lgm_p8_loop:
	ds_read_b128 v[200:203], v132 offset:16384
	ds_read_b128 v[168:171], v133
	ds_read_b128 v[204:207], v132 offset:18432
	ds_read_b128 v[208:211], v132 offset:20480
	ds_read_b128 v[212:215], v132 offset:22528
	ds_read_b128 v[172:175], v133 offset:2048
	ds_read_b128 v[176:179], v133 offset:4096
	ds_read_b128 v[180:183], v133 offset:6144
	s_setprio 1
	s_waitcnt lgkmcnt(3)
	v_mfma_f32_16x16x32_bf16 v[92:95], v[200:203], v[168:171], v[92:95]
	ds_read_b128 v[216:219], v130 offset:16384
	v_mfma_f32_16x16x32_bf16 v[88:91], v[204:207], v[168:171], v[88:91]
	ds_read_b128 v[184:187], v131
	v_mfma_f32_16x16x32_bf16 v[84:87], v[208:211], v[168:171], v[84:87]
	ds_read_b128 v[220:223], v130 offset:18432
	v_mfma_f32_16x16x32_bf16 v[146:149], v[212:215], v[168:171], v[146:149]
	ds_read_b128 v[224:227], v130 offset:20480
	s_waitcnt lgkmcnt(4)
	v_mfma_f32_16x16x32_bf16 v[44:47], v[200:203], v[172:175], v[44:47]
	ds_read_b128 v[228:231], v130 offset:22528
	v_mfma_f32_16x16x32_bf16 v[40:43], v[204:207], v[172:175], v[40:43]
	ds_read_b128 v[188:191], v131 offset:2048
	v_mfma_f32_16x16x32_bf16 v[36:39], v[208:211], v[172:175], v[36:39]
	ds_read_b128 v[192:195], v131 offset:4096
	v_mfma_f32_16x16x32_bf16 v[32:35], v[212:215], v[172:175], v[32:35]
	ds_read_b128 v[196:199], v131 offset:6144
	v_mfma_f32_16x16x32_bf16 v[28:31], v[200:203], v[176:179], v[28:31]
	s_waitcnt vmcnt(8)
	ds_write_b128 v166, v[80:83] offset:32768
	v_mfma_f32_16x16x32_bf16 v[24:27], v[204:207], v[176:179], v[24:27]
	ds_write_b128 v166, v[134:137] offset:49152
	v_mfma_f32_16x16x32_bf16 v[20:23], v[208:211], v[176:179], v[20:23]
	ds_write_b128 v166, v[116:119] offset:36864
	v_mfma_f32_16x16x32_bf16 v[16:19], v[212:215], v[176:179], v[16:19]
	ds_write_b128 v166, v[138:141] offset:53248
	v_mfma_f32_16x16x32_bf16 v[12:15], v[200:203], v[180:183], v[12:15]
	ds_write_b128 v166, v[120:123] offset:40960
	v_mfma_f32_16x16x32_bf16 v[8:11], v[204:207], v[180:183], v[8:11]
	ds_write_b128 v166, v[142:145] offset:57344
	v_mfma_f32_16x16x32_bf16 v[4:7], v[208:211], v[180:183], v[4:7]
	ds_write_b128 v166, v[124:127] offset:45056
	v_mfma_f32_16x16x32_bf16 v[0:3], v[212:215], v[180:183], v[0:3]
	s_waitcnt lgkmcnt(8)
	ds_write_b128 v166, v[150:153] offset:61440
	v_mfma_f32_16x16x32_bf16 v[92:95], v[216:219], v[184:187], v[92:95]
	v_mfma_f32_16x16x32_bf16 v[88:91], v[220:223], v[184:187], v[88:91]
	v_mfma_f32_16x16x32_bf16 v[84:87], v[224:227], v[184:187], v[84:87]
	v_mfma_f32_16x16x32_bf16 v[146:149], v[228:231], v[184:187], v[146:149]
	s_waitcnt lgkmcnt(8)
	v_mfma_f32_16x16x32_bf16 v[44:47], v[216:219], v[188:191], v[44:47]
	s_waitcnt lgkmcnt(0)
	global_load_dwordx4 v[80:83], v102, s[100:101] offset:384
	v_mfma_f32_16x16x32_bf16 v[40:43], v[220:223], v[188:191], v[40:43]
	global_load_dwordx4 v[134:137], v114, s[98:99] offset:384
	v_mfma_f32_16x16x32_bf16 v[36:39], v[224:227], v[188:191], v[36:39]
	global_load_dwordx4 v[116:119], v103, s[100:101] offset:384
	v_mfma_f32_16x16x32_bf16 v[32:35], v[228:231], v[188:191], v[32:35]
	global_load_dwordx4 v[138:141], v115, s[98:99] offset:384
	v_mfma_f32_16x16x32_bf16 v[28:31], v[216:219], v[192:195], v[28:31]
	global_load_dwordx4 v[120:123], v97, s[100:101] offset:384
	v_mfma_f32_16x16x32_bf16 v[24:27], v[220:223], v[192:195], v[24:27]
	global_load_dwordx4 v[142:145], v107, s[98:99] offset:384
	v_mfma_f32_16x16x32_bf16 v[20:23], v[224:227], v[192:195], v[20:23]
	global_load_dwordx4 v[124:127], v105, s[100:101] offset:384
	v_mfma_f32_16x16x32_bf16 v[16:19], v[228:231], v[192:195], v[16:19]
	global_load_dwordx4 v[150:153], v113, s[98:99] offset:384
	v_mfma_f32_16x16x32_bf16 v[12:15], v[216:219], v[196:199], v[12:15]
	v_mfma_f32_16x16x32_bf16 v[8:11], v[220:223], v[196:199], v[8:11]
	v_mfma_f32_16x16x32_bf16 v[4:7], v[224:227], v[196:199], v[4:7]
	v_mfma_f32_16x16x32_bf16 v[0:3], v[228:231], v[196:199], v[0:3]
	s_setprio 0
	s_barrier
	ds_read_b128 v[200:203], v132 offset:49152
	ds_read_b128 v[168:171], v133 offset:32768
	ds_read_b128 v[204:207], v132 offset:51200
	ds_read_b128 v[208:211], v132 offset:53248
	ds_read_b128 v[212:215], v132 offset:55296
	ds_read_b128 v[172:175], v133 offset:34816
	ds_read_b128 v[176:179], v133 offset:36864
	ds_read_b128 v[180:183], v133 offset:38912
	s_setprio 1
	s_waitcnt lgkmcnt(3)
	v_mfma_f32_16x16x32_bf16 v[92:95], v[200:203], v[168:171], v[92:95]
	ds_read_b128 v[216:219], v130 offset:49152
	v_mfma_f32_16x16x32_bf16 v[88:91], v[204:207], v[168:171], v[88:91]
	ds_read_b128 v[184:187], v131 offset:32768
	v_mfma_f32_16x16x32_bf16 v[84:87], v[208:211], v[168:171], v[84:87]
	ds_read_b128 v[220:223], v130 offset:51200
	v_mfma_f32_16x16x32_bf16 v[146:149], v[212:215], v[168:171], v[146:149]
	ds_read_b128 v[224:227], v130 offset:53248
	s_waitcnt lgkmcnt(4)
	v_mfma_f32_16x16x32_bf16 v[44:47], v[200:203], v[172:175], v[44:47]
	ds_read_b128 v[228:231], v130 offset:55296
	v_mfma_f32_16x16x32_bf16 v[40:43], v[204:207], v[172:175], v[40:43]
	ds_read_b128 v[188:191], v131 offset:34816
	v_mfma_f32_16x16x32_bf16 v[36:39], v[208:211], v[172:175], v[36:39]
	ds_read_b128 v[192:195], v131 offset:36864
	v_mfma_f32_16x16x32_bf16 v[32:35], v[212:215], v[172:175], v[32:35]
	ds_read_b128 v[196:199], v131 offset:38912
	v_mfma_f32_16x16x32_bf16 v[28:31], v[200:203], v[176:179], v[28:31]
	s_waitcnt vmcnt(8)
	ds_write_b128 v166, v[48:51]
	v_mfma_f32_16x16x32_bf16 v[24:27], v[204:207], v[176:179], v[24:27]
	ds_write_b128 v166, v[64:67] offset:16384
	v_mfma_f32_16x16x32_bf16 v[20:23], v[208:211], v[176:179], v[20:23]
	ds_write_b128 v166, v[52:55] offset:4096
	v_mfma_f32_16x16x32_bf16 v[16:19], v[212:215], v[176:179], v[16:19]
	ds_write_b128 v166, v[68:71] offset:20480
	v_mfma_f32_16x16x32_bf16 v[12:15], v[200:203], v[180:183], v[12:15]
	ds_write_b128 v166, v[56:59] offset:8192
	v_mfma_f32_16x16x32_bf16 v[8:11], v[204:207], v[180:183], v[8:11]
	ds_write_b128 v166, v[72:75] offset:24576
	v_mfma_f32_16x16x32_bf16 v[4:7], v[208:211], v[180:183], v[4:7]
	ds_write_b128 v166, v[60:63] offset:12288
	v_mfma_f32_16x16x32_bf16 v[0:3], v[212:215], v[180:183], v[0:3]
	s_waitcnt lgkmcnt(8)
	ds_write_b128 v166, v[76:79] offset:28672
	v_mfma_f32_16x16x32_bf16 v[92:95], v[216:219], v[184:187], v[92:95]
	v_mfma_f32_16x16x32_bf16 v[88:91], v[220:223], v[184:187], v[88:91]
	v_mfma_f32_16x16x32_bf16 v[84:87], v[224:227], v[184:187], v[84:87]
	v_mfma_f32_16x16x32_bf16 v[146:149], v[228:231], v[184:187], v[146:149]
	s_waitcnt lgkmcnt(8)
	v_mfma_f32_16x16x32_bf16 v[44:47], v[216:219], v[188:191], v[44:47]
	s_waitcnt lgkmcnt(0)
	global_load_dwordx4 v[48:51], v102, s[100:101] offset:512
	v_mfma_f32_16x16x32_bf16 v[40:43], v[220:223], v[188:191], v[40:43]
	global_load_dwordx4 v[64:67], v114, s[98:99] offset:512
	v_mfma_f32_16x16x32_bf16 v[36:39], v[224:227], v[188:191], v[36:39]
	global_load_dwordx4 v[52:55], v103, s[100:101] offset:512
	v_mfma_f32_16x16x32_bf16 v[32:35], v[228:231], v[188:191], v[32:35]
	global_load_dwordx4 v[68:71], v115, s[98:99] offset:512
	v_mfma_f32_16x16x32_bf16 v[28:31], v[216:219], v[192:195], v[28:31]
	global_load_dwordx4 v[56:59], v97, s[100:101] offset:512
	v_mfma_f32_16x16x32_bf16 v[24:27], v[220:223], v[192:195], v[24:27]
	global_load_dwordx4 v[72:75], v107, s[98:99] offset:512
	v_mfma_f32_16x16x32_bf16 v[20:23], v[224:227], v[192:195], v[20:23]
	global_load_dwordx4 v[60:63], v105, s[100:101] offset:512
	v_mfma_f32_16x16x32_bf16 v[16:19], v[228:231], v[192:195], v[16:19]
	global_load_dwordx4 v[76:79], v113, s[98:99] offset:512
	v_mfma_f32_16x16x32_bf16 v[12:15], v[216:219], v[196:199], v[12:15]
	v_mfma_f32_16x16x32_bf16 v[8:11], v[220:223], v[196:199], v[8:11]
	v_mfma_f32_16x16x32_bf16 v[4:7], v[224:227], v[196:199], v[4:7]
	v_mfma_f32_16x16x32_bf16 v[0:3], v[228:231], v[196:199], v[0:3]
	s_setprio 0
	s_barrier
	s_add_u32 s100, s100, 0x100
	s_addc_u32 s101, s101, 0
	s_add_u32 s98, s98, 0x100
	s_addc_u32 s99, s99, 0
	s_sub_u32 s84, s84, 1
	s_cmp_lg_u32 s84, 0
	s_cbranch_scc1 .Lgm_p8_loop
	ds_read_b128 v[200:203], v132 offset:16384
	ds_read_b128 v[168:171], v133
	ds_read_b128 v[204:207], v132 offset:18432
	ds_read_b128 v[208:211], v132 offset:20480
	ds_read_b128 v[212:215], v132 offset:22528
	ds_read_b128 v[172:175], v133 offset:2048
	ds_read_b128 v[176:179], v133 offset:4096
	ds_read_b128 v[180:183], v133 offset:6144
	s_setprio 1
	s_waitcnt lgkmcnt(3)
	v_mfma_f32_16x16x32_bf16 v[92:95], v[200:203], v[168:171], v[92:95]
	ds_read_b128 v[216:219], v130 offset:16384
	v_mfma_f32_16x16x32_bf16 v[88:91], v[204:207], v[168:171], v[88:91]
	ds_read_b128 v[184:187], v131
	v_mfma_f32_16x16x32_bf16 v[84:87], v[208:211], v[168:171], v[84:87]
	ds_read_b128 v[220:223], v130 offset:18432
	v_mfma_f32_16x16x32_bf16 v[146:149], v[212:215], v[168:171], v[146:149]
	ds_read_b128 v[224:227], v130 offset:20480
	s_waitcnt lgkmcnt(4)
	v_mfma_f32_16x16x32_bf16 v[44:47], v[200:203], v[172:175], v[44:47]
	ds_read_b128 v[228:231], v130 offset:22528
	v_mfma_f32_16x16x32_bf16 v[40:43], v[204:207], v[172:175], v[40:43]
	ds_read_b128 v[188:191], v131 offset:2048
	v_mfma_f32_16x16x32_bf16 v[36:39], v[208:211], v[172:175], v[36:39]
	ds_read_b128 v[192:195], v131 offset:4096
	v_mfma_f32_16x16x32_bf16 v[32:35], v[212:215], v[172:175], v[32:35]
	ds_read_b128 v[196:199], v131 offset:6144
	v_mfma_f32_16x16x32_bf16 v[28:31], v[200:203], v[176:179], v[28:31]
	s_waitcnt vmcnt(8)
	ds_write_b128 v166, v[80:83] offset:32768
	v_mfma_f32_16x16x32_bf16 v[24:27], v[204:207], v[176:179], v[24:27]
	ds_write_b128 v166, v[134:137] offset:49152
	v_mfma_f32_16x16x32_bf16 v[20:23], v[208:211], v[176:179], v[20:23]
	ds_write_b128 v166, v[116:119] offset:36864
	v_mfma_f32_16x16x32_bf16 v[16:19], v[212:215], v[176:179], v[16:19]
	ds_write_b128 v166, v[138:141] offset:53248
	v_mfma_f32_16x16x32_bf16 v[12:15], v[200:203], v[180:183], v[12:15]
	ds_write_b128 v166, v[120:123] offset:40960
	v_mfma_f32_16x16x32_bf16 v[8:11], v[204:207], v[180:183], v[8:11]
	ds_write_b128 v166, v[142:145] offset:57344
	v_mfma_f32_16x16x32_bf16 v[4:7], v[208:211], v[180:183], v[4:7]
	ds_write_b128 v166, v[124:127] offset:45056
	v_mfma_f32_16x16x32_bf16 v[0:3], v[212:215], v[180:183], v[0:3]
	s_waitcnt lgkmcnt(8)
	ds_write_b128 v166, v[150:153] offset:61440
	v_mfma_f32_16x16x32_bf16 v[92:95], v[216:219], v[184:187], v[92:95]
	v_mfma_f32_16x16x32_bf16 v[88:91], v[220:223], v[184:187], v[88:91]
	v_mfma_f32_16x16x32_bf16 v[84:87], v[224:227], v[184:187], v[84:87]
	v_mfma_f32_16x16x32_bf16 v[146:149], v[228:231], v[184:187], v[146:149]
	s_waitcnt lgkmcnt(8)
	v_mfma_f32_16x16x32_bf16 v[44:47], v[216:219], v[188:191], v[44:47]
	s_waitcnt lgkmcnt(0)
	global_load_dwordx4 v[80:83], v102, s[100:101] offset:384
	v_mfma_f32_16x16x32_bf16 v[40:43], v[220:223], v[188:191], v[40:43]
	global_load_dwordx4 v[134:137], v114, s[98:99] offset:384
	v_mfma_f32_16x16x32_bf16 v[36:39], v[224:227], v[188:191], v[36:39]
	global_load_dwordx4 v[116:119], v103, s[100:101] offset:384
	v_mfma_f32_16x16x32_bf16 v[32:35], v[228:231], v[188:191], v[32:35]
	global_load_dwordx4 v[138:141], v115, s[98:99] offset:384
	v_mfma_f32_16x16x32_bf16 v[28:31], v[216:219], v[192:195], v[28:31]
	global_load_dwordx4 v[120:123], v97, s[100:101] offset:384
	v_mfma_f32_16x16x32_bf16 v[24:27], v[220:223], v[192:195], v[24:27]
	global_load_dwordx4 v[142:145], v107, s[98:99] offset:384
	v_mfma_f32_16x16x32_bf16 v[20:23], v[224:227], v[192:195], v[20:23]
	global_load_dwordx4 v[124:127], v105, s[100:101] offset:384
	v_mfma_f32_16x16x32_bf16 v[16:19], v[228:231], v[192:195], v[16:19]
	global_load_dwordx4 v[150:153], v113, s[98:99] offset:384
	v_mfma_f32_16x16x32_bf16 v[12:15], v[216:219], v[196:199], v[12:15]
	v_mfma_f32_16x16x32_bf16 v[8:11], v[220:223], v[196:199], v[8:11]
	v_mfma_f32_16x16x32_bf16 v[4:7], v[224:227], v[196:199], v[4:7]
	v_mfma_f32_16x16x32_bf16 v[0:3], v[228:231], v[196:199], v[0:3]
	s_setprio 0
	s_barrier
	ds_read_b128 v[200:203], v132 offset:49152
	ds_read_b128 v[168:171], v133 offset:32768
	ds_read_b128 v[204:207], v132 offset:51200
	ds_read_b128 v[208:211], v132 offset:53248
	ds_read_b128 v[212:215], v132 offset:55296
	ds_read_b128 v[172:175], v133 offset:34816
	ds_read_b128 v[176:179], v133 offset:36864
	ds_read_b128 v[180:183], v133 offset:38912
	s_setprio 1
	s_waitcnt lgkmcnt(3)
	v_mfma_f32_16x16x32_bf16 v[92:95], v[200:203], v[168:171], v[92:95]
	ds_read_b128 v[216:219], v130 offset:49152
	v_mfma_f32_16x16x32_bf16 v[88:91], v[204:207], v[168:171], v[88:91]
	ds_read_b128 v[184:187], v131 offset:32768
	v_mfma_f32_16x16x32_bf16 v[84:87], v[208:211], v[168:171], v[84:87]
	ds_read_b128 v[220:223], v130 offset:51200
	v_mfma_f32_16x16x32_bf16 v[146:149], v[212:215], v[168:171], v[146:149]
	ds_read_b128 v[224:227], v130 offset:53248
	s_waitcnt lgkmcnt(4)
	v_mfma_f32_16x16x32_bf16 v[44:47], v[200:203], v[172:175], v[44:47]
	ds_read_b128 v[228:231], v130 offset:55296
	v_mfma_f32_16x16x32_bf16 v[40:43], v[204:207], v[172:175], v[40:43]
	ds_read_b128 v[188:191], v131 offset:34816
	v_mfma_f32_16x16x32_bf16 v[36:39], v[208:211], v[172:175], v[36:39]
	ds_read_b128 v[192:195], v131 offset:36864
	v_mfma_f32_16x16x32_bf16 v[32:35], v[212:215], v[172:175], v[32:35]
	ds_read_b128 v[196:199], v131 offset:38912
	v_mfma_f32_16x16x32_bf16 v[28:31], v[200:203], v[176:179], v[28:31]
	s_waitcnt vmcnt(8)
	ds_write_b128 v166, v[48:51]
	v_mfma_f32_16x16x32_bf16 v[24:27], v[204:207], v[176:179], v[24:27]
	ds_write_b128 v166, v[64:67] offset:16384
	v_mfma_f32_16x16x32_bf16 v[20:23], v[208:211], v[176:179], v[20:23]
	ds_write_b128 v166, v[52:55] offset:4096
	v_mfma_f32_16x16x32_bf16 v[16:19], v[212:215], v[176:179], v[16:19]
	ds_write_b128 v166, v[68:71] offset:20480
	v_mfma_f32_16x16x32_bf16 v[12:15], v[200:203], v[180:183], v[12:15]
	ds_write_b128 v166, v[56:59] offset:8192
	v_mfma_f32_16x16x32_bf16 v[8:11], v[204:207], v[180:183], v[8:11]
	ds_write_b128 v166, v[72:75] offset:24576
	v_mfma_f32_16x16x32_bf16 v[4:7], v[208:211], v[180:183], v[4:7]
	ds_write_b128 v166, v[60:63] offset:12288
	v_mfma_f32_16x16x32_bf16 v[0:3], v[212:215], v[180:183], v[0:3]
	s_waitcnt lgkmcnt(8)
	ds_write_b128 v166, v[76:79] offset:28672
	v_mfma_f32_16x16x32_bf16 v[92:95], v[216:219], v[184:187], v[92:95]
	v_mfma_f32_16x16x32_bf16 v[88:91], v[220:223], v[184:187], v[88:91]
	v_mfma_f32_16x16x32_bf16 v[84:87], v[224:227], v[184:187], v[84:87]
	v_mfma_f32_16x16x32_bf16 v[146:149], v[228:231], v[184:187], v[146:149]
	s_waitcnt lgkmcnt(8)
	v_mfma_f32_16x16x32_bf16 v[44:47], v[216:219], v[188:191], v[44:47]
	v_mfma_f32_16x16x32_bf16 v[40:43], v[220:223], v[188:191], v[40:43]
	v_mfma_f32_16x16x32_bf16 v[36:39], v[224:227], v[188:191], v[36:39]
	v_mfma_f32_16x16x32_bf16 v[32:35], v[228:231], v[188:191], v[32:35]
	v_mfma_f32_16x16x32_bf16 v[28:31], v[216:219], v[192:195], v[28:31]
	v_mfma_f32_16x16x32_bf16 v[24:27], v[220:223], v[192:195], v[24:27]
	v_mfma_f32_16x16x32_bf16 v[20:23], v[224:227], v[192:195], v[20:23]
	v_mfma_f32_16x16x32_bf16 v[16:19], v[228:231], v[192:195], v[16:19]
	v_mfma_f32_16x16x32_bf16 v[12:15], v[216:219], v[196:199], v[12:15]
	v_mfma_f32_16x16x32_bf16 v[8:11], v[220:223], v[196:199], v[8:11]
	v_mfma_f32_16x16x32_bf16 v[4:7], v[224:227], v[196:199], v[4:7]
	v_mfma_f32_16x16x32_bf16 v[0:3], v[228:231], v[196:199], v[0:3]
	s_setprio 0
	s_waitcnt lgkmcnt(0)
	s_barrier
	ds_read_b128 v[200:203], v132 offset:16384
	ds_read_b128 v[168:171], v133
	ds_read_b128 v[204:207], v132 offset:18432
	ds_read_b128 v[208:211], v132 offset:20480
	ds_read_b128 v[212:215], v132 offset:22528
	ds_read_b128 v[172:175], v133 offset:2048
	ds_read_b128 v[176:179], v133 offset:4096
	ds_read_b128 v[180:183], v133 offset:6144
	s_setprio 1
	s_waitcnt lgkmcnt(3)
	v_mfma_f32_16x16x32_bf16 v[92:95], v[200:203], v[168:171], v[92:95]
	ds_read_b128 v[216:219], v130 offset:16384
	v_mfma_f32_16x16x32_bf16 v[88:91], v[204:207], v[168:171], v[88:91]
	ds_read_b128 v[184:187], v131
	v_mfma_f32_16x16x32_bf16 v[84:87], v[208:211], v[168:171], v[84:87]
	ds_read_b128 v[220:223], v130 offset:18432
	v_mfma_f32_16x16x32_bf16 v[146:149], v[212:215], v[168:171], v[146:149]
	ds_read_b128 v[224:227], v130 offset:20480
	s_waitcnt lgkmcnt(4)
	v_mfma_f32_16x16x32_bf16 v[44:47], v[200:203], v[172:175], v[44:47]
	ds_read_b128 v[228:231], v130 offset:22528
	v_mfma_f32_16x16x32_bf16 v[40:43], v[204:207], v[172:175], v[40:43]
	ds_read_b128 v[188:191], v131 offset:2048
	v_mfma_f32_16x16x32_bf16 v[36:39], v[208:211], v[172:175], v[36:39]
	ds_read_b128 v[192:195], v131 offset:4096
	v_mfma_f32_16x16x32_bf16 v[32:35], v[212:215], v[172:175], v[32:35]
	ds_read_b128 v[196:199], v131 offset:6144
	v_mfma_f32_16x16x32_bf16 v[28:31], v[200:203], v[176:179], v[28:31]
	s_waitcnt vmcnt(0)
	ds_write_b128 v166, v[80:83] offset:32768
	v_mfma_f32_16x16x32_bf16 v[24:27], v[204:207], v[176:179], v[24:27]
	ds_write_b128 v166, v[134:137] offset:49152
	v_mfma_f32_16x16x32_bf16 v[20:23], v[208:211], v[176:179], v[20:23]
	ds_write_b128 v166, v[116:119] offset:36864
	v_mfma_f32_16x16x32_bf16 v[16:19], v[212:215], v[176:179], v[16:19]
	ds_write_b128 v166, v[138:141] offset:53248
	v_mfma_f32_16x16x32_bf16 v[12:15], v[200:203], v[180:183], v[12:15]
	ds_write_b128 v166, v[120:123] offset:40960
	v_mfma_f32_16x16x32_bf16 v[8:11], v[204:207], v[180:183], v[8:11]
	ds_write_b128 v166, v[142:145] offset:57344
	v_mfma_f32_16x16x32_bf16 v[4:7], v[208:211], v[180:183], v[4:7]
	ds_write_b128 v166, v[124:127] offset:45056
	v_mfma_f32_16x16x32_bf16 v[0:3], v[212:215], v[180:183], v[0:3]
	s_waitcnt lgkmcnt(8)
	ds_write_b128 v166, v[150:153] offset:61440
	v_mfma_f32_16x16x32_bf16 v[92:95], v[216:219], v[184:187], v[92:95]
	v_mfma_f32_16x16x32_bf16 v[88:91], v[220:223], v[184:187], v[88:91]
	v_mfma_f32_16x16x32_bf16 v[84:87], v[224:227], v[184:187], v[84:87]
	v_mfma_f32_16x16x32_bf16 v[146:149], v[228:231], v[184:187], v[146:149]
	s_waitcnt lgkmcnt(8)
	v_mfma_f32_16x16x32_bf16 v[44:47], v[216:219], v[188:191], v[44:47]
	v_mfma_f32_16x16x32_bf16 v[40:43], v[220:223], v[188:191], v[40:43]
	v_mfma_f32_16x16x32_bf16 v[36:39], v[224:227], v[188:191], v[36:39]
	v_mfma_f32_16x16x32_bf16 v[32:35], v[228:231], v[188:191], v[32:35]
	v_mfma_f32_16x16x32_bf16 v[28:31], v[216:219], v[192:195], v[28:31]
	v_mfma_f32_16x16x32_bf16 v[24:27], v[220:223], v[192:195], v[24:27]
	v_mfma_f32_16x16x32_bf16 v[20:23], v[224:227], v[192:195], v[20:23]
	v_mfma_f32_16x16x32_bf16 v[16:19], v[228:231], v[192:195], v[16:19]
	v_mfma_f32_16x16x32_bf16 v[12:15], v[216:219], v[196:199], v[12:15]
	v_mfma_f32_16x16x32_bf16 v[8:11], v[220:223], v[196:199], v[8:11]
	v_mfma_f32_16x16x32_bf16 v[4:7], v[224:227], v[196:199], v[4:7]
	v_mfma_f32_16x16x32_bf16 v[0:3], v[228:231], v[196:199], v[0:3]
	s_setprio 0
	s_waitcnt lgkmcnt(0)
	s_barrier
	ds_read_b128 v[200:203], v132 offset:49152
	ds_read_b128 v[168:171], v133 offset:32768
	ds_read_b128 v[204:207], v132 offset:51200
	ds_read_b128 v[208:211], v132 offset:53248
	ds_read_b128 v[212:215], v132 offset:55296
	ds_read_b128 v[172:175], v133 offset:34816
	ds_read_b128 v[176:179], v133 offset:36864
	ds_read_b128 v[180:183], v133 offset:38912
	s_setprio 1
	s_waitcnt lgkmcnt(3)
	v_mfma_f32_16x16x32_bf16 v[92:95], v[200:203], v[168:171], v[92:95]
	ds_read_b128 v[216:219], v130 offset:49152
	v_mfma_f32_16x16x32_bf16 v[88:91], v[204:207], v[168:171], v[88:91]
	ds_read_b128 v[184:187], v131 offset:32768
	v_mfma_f32_16x16x32_bf16 v[84:87], v[208:211], v[168:171], v[84:87]
	ds_read_b128 v[220:223], v130 offset:51200
	v_mfma_f32_16x16x32_bf16 v[146:149], v[212:215], v[168:171], v[146:149]
	ds_read_b128 v[224:227], v130 offset:53248
	s_waitcnt lgkmcnt(4)
	v_mfma_f32_16x16x32_bf16 v[44:47], v[200:203], v[172:175], v[44:47]
	ds_read_b128 v[228:231], v130 offset:55296
	v_mfma_f32_16x16x32_bf16 v[40:43], v[204:207], v[172:175], v[40:43]
	ds_read_b128 v[188:191], v131 offset:34816
	v_mfma_f32_16x16x32_bf16 v[36:39], v[208:211], v[172:175], v[36:39]
	ds_read_b128 v[192:195], v131 offset:36864
	v_mfma_f32_16x16x32_bf16 v[32:35], v[212:215], v[172:175], v[32:35]
	ds_read_b128 v[196:199], v131 offset:38912
	v_mfma_f32_16x16x32_bf16 v[28:31], v[200:203], v[176:179], v[28:31]
	v_mfma_f32_16x16x32_bf16 v[24:27], v[204:207], v[176:179], v[24:27]
	v_mfma_f32_16x16x32_bf16 v[20:23], v[208:211], v[176:179], v[20:23]
	v_mfma_f32_16x16x32_bf16 v[16:19], v[212:215], v[176:179], v[16:19]
	v_mfma_f32_16x16x32_bf16 v[12:15], v[200:203], v[180:183], v[12:15]
	v_mfma_f32_16x16x32_bf16 v[8:11], v[204:207], v[180:183], v[8:11]
	v_mfma_f32_16x16x32_bf16 v[4:7], v[208:211], v[180:183], v[4:7]
	v_mfma_f32_16x16x32_bf16 v[0:3], v[212:215], v[180:183], v[0:3]
	s_waitcnt lgkmcnt(3)
	v_mfma_f32_16x16x32_bf16 v[92:95], v[216:219], v[184:187], v[92:95]
	v_mfma_f32_16x16x32_bf16 v[88:91], v[220:223], v[184:187], v[88:91]
	v_mfma_f32_16x16x32_bf16 v[84:87], v[224:227], v[184:187], v[84:87]
	v_mfma_f32_16x16x32_bf16 v[146:149], v[228:231], v[184:187], v[146:149]
	s_waitcnt lgkmcnt(0)
	v_mfma_f32_16x16x32_bf16 v[44:47], v[216:219], v[188:191], v[44:47]
	v_mfma_f32_16x16x32_bf16 v[40:43], v[220:223], v[188:191], v[40:43]
	v_mfma_f32_16x16x32_bf16 v[36:39], v[224:227], v[188:191], v[36:39]
	v_mfma_f32_16x16x32_bf16 v[32:35], v[228:231], v[188:191], v[32:35]
	v_mfma_f32_16x16x32_bf16 v[28:31], v[216:219], v[192:195], v[28:31]
	v_mfma_f32_16x16x32_bf16 v[24:27], v[220:223], v[192:195], v[24:27]
	v_mfma_f32_16x16x32_bf16 v[20:23], v[224:227], v[192:195], v[20:23]
	v_mfma_f32_16x16x32_bf16 v[16:19], v[228:231], v[192:195], v[16:19]
	v_mfma_f32_16x16x32_bf16 v[12:15], v[216:219], v[196:199], v[12:15]
	v_mfma_f32_16x16x32_bf16 v[8:11], v[220:223], v[196:199], v[8:11]
	v_mfma_f32_16x16x32_bf16 v[4:7], v[224:227], v[196:199], v[4:7]
	v_mfma_f32_16x16x32_bf16 v[0:3], v[228:231], v[196:199], v[0:3]
	s_setprio 0
	s_nop 7
	v_add_u32_e32 v102, s5, v167
	v_ashrrev_i32_e32 v103, 31, v102
	v_lshlrev_b64 v[48:49], 12, v[102:103]
	v_or_b32_e32 v64, 16, v102
	v_or_b32_e32 v80, 32, v102
	v_or_b32_e32 v102, 48, v102
	v_ashrrev_i32_e32 v65, 31, v64
	v_ashrrev_i32_e32 v81, 31, v80
	v_ashrrev_i32_e32 v103, 31, v102
	s_ashr_i32 s5, s4, 31
	v_lshlrev_b64 v[64:65], 12, v[64:65]
	v_lshlrev_b64 v[80:81], 12, v[80:81]
	v_lshlrev_b64 v[102:103], 12, v[102:103]
	v_lshl_add_u64 v[48:49], s[88:89], 0, v[48:49]
	s_lshl_b64 s[4:5], s[4:5], 2
	v_lshl_add_u64 v[64:65], s[88:89], 0, v[64:65]
	v_lshl_add_u64 v[80:81], s[88:89], 0, v[80:81]
	v_lshl_add_u64 v[102:103], s[88:89], 0, v[102:103]
	v_lshl_add_u64 v[48:49], v[48:49], 0, s[4:5]
	v_lshl_add_u64 v[64:65], v[64:65], 0, s[4:5]
	v_lshl_add_u64 v[80:81], v[80:81], 0, s[4:5]
	v_lshl_add_u64 v[102:103], v[102:103], 0, s[4:5]
	v_lshl_add_u64 v[48:49], v[48:49], 0, v[110:111]
	v_lshlrev_b32_e32 v126, 2, v108
	v_mov_b32_e32 v127, v111
	v_lshl_add_u64 v[64:65], v[64:65], 0, v[110:111]
	v_lshl_add_u64 v[80:81], v[80:81], 0, v[110:111]
	v_lshl_add_u64 v[102:103], v[102:103], 0, v[110:111]
	v_lshl_add_u64 v[150:151], v[48:49], 0, v[126:127]
	v_lshl_add_u64 v[152:153], v[64:65], 0, v[126:127]
	v_lshl_add_u64 v[164:165], v[80:81], 0, v[126:127]
	v_lshl_add_u64 v[102:103], v[102:103], 0, v[126:127]
	global_load_dwordx4 v[48:51], v[150:151], off
	global_load_dwordx4 v[52:55], v[150:151], off offset:64
	global_load_dwordx4 v[56:59], v[150:151], off offset:128
	global_load_dwordx4 v[60:63], v[150:151], off offset:192
	global_load_dwordx4 v[64:67], v[152:153], off
	global_load_dwordx4 v[68:71], v[152:153], off offset:64
	global_load_dwordx4 v[72:75], v[152:153], off offset:128
	global_load_dwordx4 v[76:79], v[152:153], off offset:192
	global_load_dwordx4 v[80:83], v[164:165], off
	global_load_dwordx4 v[114:117], v[164:165], off offset:64
	global_load_dwordx4 v[118:121], v[164:165], off offset:128
	global_load_dwordx4 v[122:125], v[164:165], off offset:192
	global_load_dwordx4 v[126:129], v[102:103], off
	global_load_dwordx4 v[134:137], v[102:103], off offset:64
	global_load_dwordx4 v[138:141], v[102:103], off offset:128
	global_load_dwordx4 v[142:145], v[102:103], off offset:192
	s_mov_b32 s8, 0
	s_waitcnt vmcnt(15)
	v_pk_add_f32 v[48:49], v[92:93], v[48:49]
	v_pk_add_f32 v[50:51], v[94:95], v[50:51]
	s_waitcnt vmcnt(11)
	v_pk_add_f32 v[44:45], v[44:45], v[64:65]
	v_pk_add_f32 v[46:47], v[46:47], v[66:67]
	v_pk_add_f32 v[52:53], v[88:89], v[52:53]
	s_waitcnt vmcnt(1)
	v_pk_add_f32 v[4:5], v[4:5], v[138:139]
	v_pk_add_f32 v[6:7], v[6:7], v[140:141]
	s_waitcnt vmcnt(0)
	v_pk_add_f32 v[0:1], v[0:1], v[142:143]
	v_pk_add_f32 v[2:3], v[2:3], v[144:145]
	v_pk_add_f32 v[54:55], v[90:91], v[54:55]
	v_pk_add_f32 v[56:57], v[84:85], v[56:57]
	v_pk_add_f32 v[58:59], v[86:87], v[58:59]
	v_pk_add_f32 v[60:61], v[146:147], v[60:61]
	v_pk_add_f32 v[62:63], v[148:149], v[62:63]
	global_store_dwordx4 v[150:151], v[48:51], off
	global_store_dwordx4 v[150:151], v[52:55], off offset:64
	global_store_dwordx4 v[150:151], v[56:59], off offset:128
	global_store_dwordx4 v[150:151], v[60:63], off offset:192
	v_pk_add_f32 v[40:41], v[40:41], v[68:69]
	v_pk_add_f32 v[42:43], v[42:43], v[70:71]
	v_pk_add_f32 v[36:37], v[36:37], v[72:73]
	v_pk_add_f32 v[38:39], v[38:39], v[74:75]
	v_pk_add_f32 v[32:33], v[32:33], v[76:77]
	v_pk_add_f32 v[34:35], v[34:35], v[78:79]
	v_pk_add_f32 v[28:29], v[28:29], v[80:81]
	v_pk_add_f32 v[30:31], v[30:31], v[82:83]
	v_pk_add_f32 v[24:25], v[24:25], v[114:115]
	v_pk_add_f32 v[26:27], v[26:27], v[116:117]
	v_pk_add_f32 v[20:21], v[20:21], v[118:119]
	v_pk_add_f32 v[22:23], v[22:23], v[120:121]
	v_pk_add_f32 v[16:17], v[16:17], v[122:123]
	v_pk_add_f32 v[18:19], v[18:19], v[124:125]
	v_pk_add_f32 v[12:13], v[12:13], v[126:127]
	v_pk_add_f32 v[14:15], v[14:15], v[128:129]
	v_pk_add_f32 v[8:9], v[8:9], v[134:135]
	v_pk_add_f32 v[10:11], v[10:11], v[136:137]
	global_store_dwordx4 v[152:153], v[44:47], off
	global_store_dwordx4 v[152:153], v[40:43], off offset:64
	global_store_dwordx4 v[152:153], v[36:39], off offset:128
	global_store_dwordx4 v[152:153], v[32:35], off offset:192
	global_store_dwordx4 v[164:165], v[28:31], off
	global_store_dwordx4 v[164:165], v[24:27], off offset:64
	global_store_dwordx4 v[164:165], v[20:23], off offset:128
	global_store_dwordx4 v[164:165], v[16:19], off offset:192
	global_store_dwordx4 v[102:103], v[12:15], off
	global_store_dwordx4 v[102:103], v[8:11], off offset:64
	global_store_dwordx4 v[102:103], v[4:7], off offset:128
	global_store_dwordx4 v[102:103], v[0:3], off offset:192
	s_mov_b64 s[4:5], -1
	s_cmp_gt_i32 s8, 3
	s_mov_b64 s[6:7], -1
	s_cbranch_scc1 .LBB0_919
